# amix unit epilogue: the 8 gate loads of each half issued together
# baseline (speedup 1.0000x reference)
.Lg2_k:
	s_waitcnt vmcnt(0)
	s_barrier
	ds_read_b128 v[148:151], v78 offset:0
	ds_read_b128 v[152:155], v78 offset:2048
	ds_read_b128 v[156:159], v78 offset:4096
	ds_read_b128 v[160:163], v78 offset:6144
	ds_read_b128 v[188:191], v79 offset:32768
	ds_read_b128 v[192:195], v79 offset:34816
	ds_read_b128 v[208:211], v79 offset:36864
	ds_read_b128 v[212:215], v79 offset:38912
	ds_read_b128 v[164:167], v78 offset:16384
	ds_read_b128 v[168:171], v78 offset:18432
	ds_read_b128 v[174:177], v78 offset:20480
	ds_read_b128 v[182:185], v78 offset:22528
	s_add_i32 m0, s58, 0xc000
	s_nop 0
	global_load_lds_dwordx4 v74, s[56:57]
	s_add_i32 m0, s58, 0xd000
	s_nop 0
	global_load_lds_dwordx4 v75, s[56:57]
	s_add_i32 m0, s58, 0xe000
	s_nop 0
	global_load_lds_dwordx4 v76, s[56:57]
	s_add_i32 m0, s58, 0xf000
	s_nop 0
	global_load_lds_dwordx4 v77, s[56:57]
	s_add_u32 s56, s56, 0x80
	s_addc_u32 s57, s57, 0
	s_setprio 1
	s_waitcnt lgkmcnt(4)
	v_mfma_f32_16x16x32_bf16 v[62:65], v[188:191], v[148:151], v[62:65]
	v_mfma_f32_16x16x32_bf16 v[58:61], v[192:195], v[148:151], v[58:61]
	v_mfma_f32_16x16x32_bf16 v[54:57], v[208:211], v[148:151], v[54:57]
	v_mfma_f32_16x16x32_bf16 v[50:53], v[212:215], v[148:151], v[50:53]
	v_mfma_f32_16x16x32_bf16 v[46:49], v[188:191], v[152:155], v[46:49]
	v_mfma_f32_16x16x32_bf16 v[42:45], v[192:195], v[152:155], v[42:45]
	v_mfma_f32_16x16x32_bf16 v[38:41], v[208:211], v[152:155], v[38:41]
	v_mfma_f32_16x16x32_bf16 v[34:37], v[212:215], v[152:155], v[34:37]
	v_mfma_f32_16x16x32_bf16 v[30:33], v[188:191], v[156:159], v[30:33]
	v_mfma_f32_16x16x32_bf16 v[26:29], v[192:195], v[156:159], v[26:29]
	v_mfma_f32_16x16x32_bf16 v[22:25], v[208:211], v[156:159], v[22:25]
	v_mfma_f32_16x16x32_bf16 v[18:21], v[212:215], v[156:159], v[18:21]
	v_mfma_f32_16x16x32_bf16 v[14:17], v[188:191], v[160:163], v[14:17]
	v_mfma_f32_16x16x32_bf16 v[10:13], v[192:195], v[160:163], v[10:13]
	v_mfma_f32_16x16x32_bf16 v[6:9], v[208:211], v[160:163], v[6:9]
	v_mfma_f32_16x16x32_bf16 v[2:5], v[212:215], v[160:163], v[2:5]
	s_waitcnt lgkmcnt(0)
	v_mfma_f32_16x16x32_bf16 v[66:69], v[188:191], v[164:167], v[66:69]
	v_mfma_f32_16x16x32_bf16 v[70:73], v[192:195], v[164:167], v[70:73]
	v_mfma_f32_16x16x32_bf16 v[82:85], v[208:211], v[164:167], v[82:85]
	v_mfma_f32_16x16x32_bf16 v[88:91], v[212:215], v[164:167], v[88:91]
	v_mfma_f32_16x16x32_bf16 v[92:95], v[188:191], v[168:171], v[92:95]
	v_mfma_f32_16x16x32_bf16 v[96:99], v[192:195], v[168:171], v[96:99]
	v_mfma_f32_16x16x32_bf16 v[100:103], v[208:211], v[168:171], v[100:103]
	v_mfma_f32_16x16x32_bf16 v[106:109], v[212:215], v[168:171], v[106:109]
	v_mfma_f32_16x16x32_bf16 v[110:113], v[188:191], v[174:177], v[110:113]
	v_mfma_f32_16x16x32_bf16 v[114:117], v[192:195], v[174:177], v[114:117]
	v_mfma_f32_16x16x32_bf16 v[118:121], v[208:211], v[174:177], v[118:121]
	v_mfma_f32_16x16x32_bf16 v[122:125], v[212:215], v[174:177], v[122:125]
	v_mfma_f32_16x16x32_bf16 v[126:129], v[188:191], v[182:185], v[126:129]
	v_mfma_f32_16x16x32_bf16 v[136:139], v[192:195], v[182:185], v[136:139]
	v_mfma_f32_16x16x32_bf16 v[140:143], v[208:211], v[182:185], v[140:143]
	v_mfma_f32_16x16x32_bf16 v[144:147], v[212:215], v[182:185], v[144:147]
	s_setprio 0
	ds_read_b128 v[148:151], v80 offset:0
	ds_read_b128 v[152:155], v80 offset:2048
	ds_read_b128 v[156:159], v80 offset:4096
	ds_read_b128 v[160:163], v80 offset:6144
	ds_read_b128 v[188:191], v81 offset:32768
	ds_read_b128 v[192:195], v81 offset:34816
	ds_read_b128 v[208:211], v81 offset:36864
	ds_read_b128 v[212:215], v81 offset:38912
	ds_read_b128 v[164:167], v80 offset:16384
	ds_read_b128 v[168:171], v80 offset:18432
	ds_read_b128 v[174:177], v80 offset:20480
	ds_read_b128 v[182:185], v80 offset:22528
	s_waitcnt lgkmcnt(0)
	s_barrier
	s_add_i32 m0, s58, 0x0
	s_nop 0
	global_load_lds_dwordx4 v74, s[50:51]
	s_add_i32 m0, s58, 0x1000
	s_nop 0
	global_load_lds_dwordx4 v75, s[50:51]
	s_add_i32 m0, s58, 0x2000
	s_nop 0
	global_load_lds_dwordx4 v76, s[50:51]
	s_add_i32 m0, s58, 0x3000
	s_nop 0
	global_load_lds_dwordx4 v77, s[50:51]
	s_add_i32 m0, s58, 0x4000
	s_nop 0
	global_load_lds_dwordx4 v74, s[52:53]
	s_add_i32 m0, s58, 0x5000
	s_nop 0
	global_load_lds_dwordx4 v75, s[52:53]
	s_add_i32 m0, s58, 0x6000
	s_nop 0
	global_load_lds_dwordx4 v76, s[52:53]
	s_add_i32 m0, s58, 0x7000
	s_nop 0
	global_load_lds_dwordx4 v77, s[52:53]
	s_add_u32 s50, s50, 0x80
	s_addc_u32 s51, s51, 0
	s_add_u32 s52, s52, 0x80
	s_addc_u32 s53, s53, 0
	s_setprio 1
	v_mfma_f32_16x16x32_bf16 v[62:65], v[188:191], v[148:151], v[62:65]
	v_mfma_f32_16x16x32_bf16 v[58:61], v[192:195], v[148:151], v[58:61]
	v_mfma_f32_16x16x32_bf16 v[54:57], v[208:211], v[148:151], v[54:57]
	v_mfma_f32_16x16x32_bf16 v[50:53], v[212:215], v[148:151], v[50:53]
	v_mfma_f32_16x16x32_bf16 v[46:49], v[188:191], v[152:155], v[46:49]
	v_mfma_f32_16x16x32_bf16 v[42:45], v[192:195], v[152:155], v[42:45]
	v_mfma_f32_16x16x32_bf16 v[38:41], v[208:211], v[152:155], v[38:41]
	v_mfma_f32_16x16x32_bf16 v[34:37], v[212:215], v[152:155], v[34:37]
	v_mfma_f32_16x16x32_bf16 v[30:33], v[188:191], v[156:159], v[30:33]
	v_mfma_f32_16x16x32_bf16 v[26:29], v[192:195], v[156:159], v[26:29]
	v_mfma_f32_16x16x32_bf16 v[22:25], v[208:211], v[156:159], v[22:25]
	v_mfma_f32_16x16x32_bf16 v[18:21], v[212:215], v[156:159], v[18:21]
	v_mfma_f32_16x16x32_bf16 v[14:17], v[188:191], v[160:163], v[14:17]
	v_mfma_f32_16x16x32_bf16 v[10:13], v[192:195], v[160:163], v[10:13]
	v_mfma_f32_16x16x32_bf16 v[6:9], v[208:211], v[160:163], v[6:9]
	v_mfma_f32_16x16x32_bf16 v[2:5], v[212:215], v[160:163], v[2:5]
	v_mfma_f32_16x16x32_bf16 v[66:69], v[188:191], v[164:167], v[66:69]
	v_mfma_f32_16x16x32_bf16 v[70:73], v[192:195], v[164:167], v[70:73]
	v_mfma_f32_16x16x32_bf16 v[82:85], v[208:211], v[164:167], v[82:85]
	v_mfma_f32_16x16x32_bf16 v[88:91], v[212:215], v[164:167], v[88:91]
	v_mfma_f32_16x16x32_bf16 v[92:95], v[188:191], v[168:171], v[92:95]
	v_mfma_f32_16x16x32_bf16 v[96:99], v[192:195], v[168:171], v[96:99]
	v_mfma_f32_16x16x32_bf16 v[100:103], v[208:211], v[168:171], v[100:103]
	v_mfma_f32_16x16x32_bf16 v[106:109], v[212:215], v[168:171], v[106:109]
	v_mfma_f32_16x16x32_bf16 v[110:113], v[188:191], v[174:177], v[110:113]
	v_mfma_f32_16x16x32_bf16 v[114:117], v[192:195], v[174:177], v[114:117]
	v_mfma_f32_16x16x32_bf16 v[118:121], v[208:211], v[174:177], v[118:121]
	v_mfma_f32_16x16x32_bf16 v[122:125], v[212:215], v[174:177], v[122:125]
	v_mfma_f32_16x16x32_bf16 v[126:129], v[188:191], v[182:185], v[126:129]
	v_mfma_f32_16x16x32_bf16 v[136:139], v[192:195], v[182:185], v[136:139]
	v_mfma_f32_16x16x32_bf16 v[140:143], v[208:211], v[182:185], v[140:143]
	v_mfma_f32_16x16x32_bf16 v[144:147], v[212:215], v[182:185], v[144:147]
	s_setprio 0
	s_waitcnt vmcnt(0)
	s_barrier
	ds_read_b128 v[148:151], v78 offset:0
	ds_read_b128 v[152:155], v78 offset:2048
	ds_read_b128 v[156:159], v78 offset:4096
	ds_read_b128 v[160:163], v78 offset:6144
	ds_read_b128 v[188:191], v79 offset:49152
	ds_read_b128 v[192:195], v79 offset:51200
	ds_read_b128 v[208:211], v79 offset:53248
	ds_read_b128 v[212:215], v79 offset:55296
	ds_read_b128 v[164:167], v78 offset:16384
	ds_read_b128 v[168:171], v78 offset:18432
	ds_read_b128 v[174:177], v78 offset:20480
	ds_read_b128 v[182:185], v78 offset:22528
	s_add_i32 m0, s58, 0x8000
	s_nop 0
	global_load_lds_dwordx4 v74, s[56:57]
	s_add_i32 m0, s58, 0x9000
	s_nop 0
	global_load_lds_dwordx4 v75, s[56:57]
	s_add_i32 m0, s58, 0xa000
	s_nop 0
	global_load_lds_dwordx4 v76, s[56:57]
	s_add_i32 m0, s58, 0xb000
	s_nop 0
	global_load_lds_dwordx4 v77, s[56:57]
	s_add_u32 s56, s56, 0x80
	s_addc_u32 s57, s57, 0
	s_setprio 1
	s_waitcnt lgkmcnt(4)
	v_mfma_f32_16x16x32_bf16 v[62:65], v[188:191], v[148:151], v[62:65]
	v_mfma_f32_16x16x32_bf16 v[58:61], v[192:195], v[148:151], v[58:61]
	v_mfma_f32_16x16x32_bf16 v[54:57], v[208:211], v[148:151], v[54:57]
	v_mfma_f32_16x16x32_bf16 v[50:53], v[212:215], v[148:151], v[50:53]
	v_mfma_f32_16x16x32_bf16 v[46:49], v[188:191], v[152:155], v[46:49]
	v_mfma_f32_16x16x32_bf16 v[42:45], v[192:195], v[152:155], v[42:45]
	v_mfma_f32_16x16x32_bf16 v[38:41], v[208:211], v[152:155], v[38:41]
	v_mfma_f32_16x16x32_bf16 v[34:37], v[212:215], v[152:155], v[34:37]
	v_mfma_f32_16x16x32_bf16 v[30:33], v[188:191], v[156:159], v[30:33]
	v_mfma_f32_16x16x32_bf16 v[26:29], v[192:195], v[156:159], v[26:29]
	v_mfma_f32_16x16x32_bf16 v[22:25], v[208:211], v[156:159], v[22:25]
	v_mfma_f32_16x16x32_bf16 v[18:21], v[212:215], v[156:159], v[18:21]
	v_mfma_f32_16x16x32_bf16 v[14:17], v[188:191], v[160:163], v[14:17]
	v_mfma_f32_16x16x32_bf16 v[10:13], v[192:195], v[160:163], v[10:13]
	v_mfma_f32_16x16x32_bf16 v[6:9], v[208:211], v[160:163], v[6:9]
	v_mfma_f32_16x16x32_bf16 v[2:5], v[212:215], v[160:163], v[2:5]
	s_waitcnt lgkmcnt(0)
	v_mfma_f32_16x16x32_bf16 v[66:69], v[188:191], v[164:167], v[66:69]
	v_mfma_f32_16x16x32_bf16 v[70:73], v[192:195], v[164:167], v[70:73]
	v_mfma_f32_16x16x32_bf16 v[82:85], v[208:211], v[164:167], v[82:85]
	v_mfma_f32_16x16x32_bf16 v[88:91], v[212:215], v[164:167], v[88:91]
	v_mfma_f32_16x16x32_bf16 v[92:95], v[188:191], v[168:171], v[92:95]
	v_mfma_f32_16x16x32_bf16 v[96:99], v[192:195], v[168:171], v[96:99]
	v_mfma_f32_16x16x32_bf16 v[100:103], v[208:211], v[168:171], v[100:103]
	v_mfma_f32_16x16x32_bf16 v[106:109], v[212:215], v[168:171], v[106:109]
	v_mfma_f32_16x16x32_bf16 v[110:113], v[188:191], v[174:177], v[110:113]
	v_mfma_f32_16x16x32_bf16 v[114:117], v[192:195], v[174:177], v[114:117]
	v_mfma_f32_16x16x32_bf16 v[118:121], v[208:211], v[174:177], v[118:121]
	v_mfma_f32_16x16x32_bf16 v[122:125], v[212:215], v[174:177], v[122:125]
	v_mfma_f32_16x16x32_bf16 v[126:129], v[188:191], v[182:185], v[126:129]
	v_mfma_f32_16x16x32_bf16 v[136:139], v[192:195], v[182:185], v[136:139]
	v_mfma_f32_16x16x32_bf16 v[140:143], v[208:211], v[182:185], v[140:143]
	v_mfma_f32_16x16x32_bf16 v[144:147], v[212:215], v[182:185], v[144:147]
	s_setprio 0
	ds_read_b128 v[148:151], v80 offset:0
	ds_read_b128 v[152:155], v80 offset:2048
	ds_read_b128 v[156:159], v80 offset:4096
	ds_read_b128 v[160:163], v80 offset:6144
	ds_read_b128 v[188:191], v81 offset:49152
	ds_read_b128 v[192:195], v81 offset:51200
	ds_read_b128 v[208:211], v81 offset:53248
	ds_read_b128 v[212:215], v81 offset:55296
	ds_read_b128 v[164:167], v80 offset:16384
	ds_read_b128 v[168:171], v80 offset:18432
	ds_read_b128 v[174:177], v80 offset:20480
	ds_read_b128 v[182:185], v80 offset:22528
	s_waitcnt lgkmcnt(0)
	s_barrier
	s_add_i32 m0, s58, 0x0
	s_nop 0
	global_load_lds_dwordx4 v74, s[50:51]
	s_add_i32 m0, s58, 0x1000
	s_nop 0
	global_load_lds_dwordx4 v75, s[50:51]
	s_add_i32 m0, s58, 0x2000
	s_nop 0
	global_load_lds_dwordx4 v76, s[50:51]
	s_add_i32 m0, s58, 0x3000
	s_nop 0
	global_load_lds_dwordx4 v77, s[50:51]
	s_add_i32 m0, s58, 0x4000
	s_nop 0
	global_load_lds_dwordx4 v74, s[52:53]
	s_add_i32 m0, s58, 0x5000
	s_nop 0
	global_load_lds_dwordx4 v75, s[52:53]
	s_add_i32 m0, s58, 0x6000
	s_nop 0
	global_load_lds_dwordx4 v76, s[52:53]
	s_add_i32 m0, s58, 0x7000
	s_nop 0
	global_load_lds_dwordx4 v77, s[52:53]
	s_add_u32 s50, s50, 0x80
	s_addc_u32 s51, s51, 0
	s_add_u32 s52, s52, 0x80
	s_addc_u32 s53, s53, 0
	s_setprio 1
	v_mfma_f32_16x16x32_bf16 v[62:65], v[188:191], v[148:151], v[62:65]
	v_mfma_f32_16x16x32_bf16 v[58:61], v[192:195], v[148:151], v[58:61]
	v_mfma_f32_16x16x32_bf16 v[54:57], v[208:211], v[148:151], v[54:57]
	v_mfma_f32_16x16x32_bf16 v[50:53], v[212:215], v[148:151], v[50:53]
	v_mfma_f32_16x16x32_bf16 v[46:49], v[188:191], v[152:155], v[46:49]
	v_mfma_f32_16x16x32_bf16 v[42:45], v[192:195], v[152:155], v[42:45]
	v_mfma_f32_16x16x32_bf16 v[38:41], v[208:211], v[152:155], v[38:41]
	v_mfma_f32_16x16x32_bf16 v[34:37], v[212:215], v[152:155], v[34:37]
	v_mfma_f32_16x16x32_bf16 v[30:33], v[188:191], v[156:159], v[30:33]
	v_mfma_f32_16x16x32_bf16 v[26:29], v[192:195], v[156:159], v[26:29]
	v_mfma_f32_16x16x32_bf16 v[22:25], v[208:211], v[156:159], v[22:25]
	v_mfma_f32_16x16x32_bf16 v[18:21], v[212:215], v[156:159], v[18:21]
	v_mfma_f32_16x16x32_bf16 v[14:17], v[188:191], v[160:163], v[14:17]
	v_mfma_f32_16x16x32_bf16 v[10:13], v[192:195], v[160:163], v[10:13]
	v_mfma_f32_16x16x32_bf16 v[6:9], v[208:211], v[160:163], v[6:9]
	v_mfma_f32_16x16x32_bf16 v[2:5], v[212:215], v[160:163], v[2:5]
	v_mfma_f32_16x16x32_bf16 v[66:69], v[188:191], v[164:167], v[66:69]
	v_mfma_f32_16x16x32_bf16 v[70:73], v[192:195], v[164:167], v[70:73]
	v_mfma_f32_16x16x32_bf16 v[82:85], v[208:211], v[164:167], v[82:85]
	v_mfma_f32_16x16x32_bf16 v[88:91], v[212:215], v[164:167], v[88:91]
	v_mfma_f32_16x16x32_bf16 v[92:95], v[188:191], v[168:171], v[92:95]
	v_mfma_f32_16x16x32_bf16 v[96:99], v[192:195], v[168:171], v[96:99]
	v_mfma_f32_16x16x32_bf16 v[100:103], v[208:211], v[168:171], v[100:103]
	v_mfma_f32_16x16x32_bf16 v[106:109], v[212:215], v[168:171], v[106:109]
	v_mfma_f32_16x16x32_bf16 v[110:113], v[188:191], v[174:177], v[110:113]
	v_mfma_f32_16x16x32_bf16 v[114:117], v[192:195], v[174:177], v[114:117]
	v_mfma_f32_16x16x32_bf16 v[118:121], v[208:211], v[174:177], v[118:121]
	v_mfma_f32_16x16x32_bf16 v[122:125], v[212:215], v[174:177], v[122:125]
	v_mfma_f32_16x16x32_bf16 v[126:129], v[188:191], v[182:185], v[126:129]
	v_mfma_f32_16x16x32_bf16 v[136:139], v[192:195], v[182:185], v[136:139]
	v_mfma_f32_16x16x32_bf16 v[140:143], v[208:211], v[182:185], v[140:143]
	v_mfma_f32_16x16x32_bf16 v[144:147], v[212:215], v[182:185], v[144:147]
	s_setprio 0
	s_add_i32 s59, s59, -1
	s_cmp_lg_u32 s59, 0
	s_cbranch_scc1 .Lg2_k
	s_waitcnt vmcnt(0)
	s_barrier
	ds_read_b128 v[148:151], v78 offset:0
	ds_read_b128 v[152:155], v78 offset:2048
	ds_read_b128 v[156:159], v78 offset:4096
	ds_read_b128 v[160:163], v78 offset:6144
	ds_read_b128 v[188:191], v79 offset:32768
	ds_read_b128 v[192:195], v79 offset:34816
	ds_read_b128 v[208:211], v79 offset:36864
	ds_read_b128 v[212:215], v79 offset:38912
	ds_read_b128 v[164:167], v78 offset:16384
	ds_read_b128 v[168:171], v78 offset:18432
	ds_read_b128 v[174:177], v78 offset:20480
	ds_read_b128 v[182:185], v78 offset:22528
	s_add_i32 m0, s58, 0xc000
	s_nop 0
	global_load_lds_dwordx4 v74, s[56:57]
	s_add_i32 m0, s58, 0xd000
	s_nop 0
	global_load_lds_dwordx4 v75, s[56:57]
	s_add_i32 m0, s58, 0xe000
	s_nop 0
	global_load_lds_dwordx4 v76, s[56:57]
	s_add_i32 m0, s58, 0xf000
	s_nop 0
	global_load_lds_dwordx4 v77, s[56:57]
	s_add_u32 s56, s56, 0x80
	s_addc_u32 s57, s57, 0
	s_setprio 1
	s_waitcnt lgkmcnt(4)
	v_mfma_f32_16x16x32_bf16 v[62:65], v[188:191], v[148:151], v[62:65]
	v_mfma_f32_16x16x32_bf16 v[58:61], v[192:195], v[148:151], v[58:61]
	v_mfma_f32_16x16x32_bf16 v[54:57], v[208:211], v[148:151], v[54:57]
	v_mfma_f32_16x16x32_bf16 v[50:53], v[212:215], v[148:151], v[50:53]
	v_mfma_f32_16x16x32_bf16 v[46:49], v[188:191], v[152:155], v[46:49]
	v_mfma_f32_16x16x32_bf16 v[42:45], v[192:195], v[152:155], v[42:45]
	v_mfma_f32_16x16x32_bf16 v[38:41], v[208:211], v[152:155], v[38:41]
	v_mfma_f32_16x16x32_bf16 v[34:37], v[212:215], v[152:155], v[34:37]
	v_mfma_f32_16x16x32_bf16 v[30:33], v[188:191], v[156:159], v[30:33]
	v_mfma_f32_16x16x32_bf16 v[26:29], v[192:195], v[156:159], v[26:29]
	v_mfma_f32_16x16x32_bf16 v[22:25], v[208:211], v[156:159], v[22:25]
	v_mfma_f32_16x16x32_bf16 v[18:21], v[212:215], v[156:159], v[18:21]
	v_mfma_f32_16x16x32_bf16 v[14:17], v[188:191], v[160:163], v[14:17]
	v_mfma_f32_16x16x32_bf16 v[10:13], v[192:195], v[160:163], v[10:13]
	v_mfma_f32_16x16x32_bf16 v[6:9], v[208:211], v[160:163], v[6:9]
	v_mfma_f32_16x16x32_bf16 v[2:5], v[212:215], v[160:163], v[2:5]
	s_waitcnt lgkmcnt(0)
	v_mfma_f32_16x16x32_bf16 v[66:69], v[188:191], v[164:167], v[66:69]
	v_mfma_f32_16x16x32_bf16 v[70:73], v[192:195], v[164:167], v[70:73]
	v_mfma_f32_16x16x32_bf16 v[82:85], v[208:211], v[164:167], v[82:85]
	v_mfma_f32_16x16x32_bf16 v[88:91], v[212:215], v[164:167], v[88:91]
	v_mfma_f32_16x16x32_bf16 v[92:95], v[188:191], v[168:171], v[92:95]
	v_mfma_f32_16x16x32_bf16 v[96:99], v[192:195], v[168:171], v[96:99]
	v_mfma_f32_16x16x32_bf16 v[100:103], v[208:211], v[168:171], v[100:103]
	v_mfma_f32_16x16x32_bf16 v[106:109], v[212:215], v[168:171], v[106:109]
	v_mfma_f32_16x16x32_bf16 v[110:113], v[188:191], v[174:177], v[110:113]
	v_mfma_f32_16x16x32_bf16 v[114:117], v[192:195], v[174:177], v[114:117]
	v_mfma_f32_16x16x32_bf16 v[118:121], v[208:211], v[174:177], v[118:121]
	v_mfma_f32_16x16x32_bf16 v[122:125], v[212:215], v[174:177], v[122:125]
	v_mfma_f32_16x16x32_bf16 v[126:129], v[188:191], v[182:185], v[126:129]
	v_mfma_f32_16x16x32_bf16 v[136:139], v[192:195], v[182:185], v[136:139]
	v_mfma_f32_16x16x32_bf16 v[140:143], v[208:211], v[182:185], v[140:143]
	v_mfma_f32_16x16x32_bf16 v[144:147], v[212:215], v[182:185], v[144:147]
	s_setprio 0
	ds_read_b128 v[148:151], v80 offset:0
	ds_read_b128 v[152:155], v80 offset:2048
	ds_read_b128 v[156:159], v80 offset:4096
	ds_read_b128 v[160:163], v80 offset:6144
	ds_read_b128 v[188:191], v81 offset:32768
	ds_read_b128 v[192:195], v81 offset:34816
	ds_read_b128 v[208:211], v81 offset:36864
	ds_read_b128 v[212:215], v81 offset:38912
	ds_read_b128 v[164:167], v80 offset:16384
	ds_read_b128 v[168:171], v80 offset:18432
	ds_read_b128 v[174:177], v80 offset:20480
	ds_read_b128 v[182:185], v80 offset:22528
	s_waitcnt lgkmcnt(0)
	s_barrier
	s_add_i32 m0, s58, 0x0
	s_nop 0
	global_load_lds_dwordx4 v74, s[50:51]
	s_add_i32 m0, s58, 0x1000
	s_nop 0
	global_load_lds_dwordx4 v75, s[50:51]
	s_add_i32 m0, s58, 0x2000
	s_nop 0
	global_load_lds_dwordx4 v76, s[50:51]
	s_add_i32 m0, s58, 0x3000
	s_nop 0
	global_load_lds_dwordx4 v77, s[50:51]
	s_add_i32 m0, s58, 0x4000
	s_nop 0
	global_load_lds_dwordx4 v74, s[52:53]
	s_add_i32 m0, s58, 0x5000
	s_nop 0
	global_load_lds_dwordx4 v75, s[52:53]
	s_add_i32 m0, s58, 0x6000
	s_nop 0
	global_load_lds_dwordx4 v76, s[52:53]
	s_add_i32 m0, s58, 0x7000
	s_nop 0
	global_load_lds_dwordx4 v77, s[52:53]
	s_add_u32 s50, s50, 0x80
	s_addc_u32 s51, s51, 0
	s_add_u32 s52, s52, 0x80
	s_addc_u32 s53, s53, 0
	s_setprio 1
	v_mfma_f32_16x16x32_bf16 v[62:65], v[188:191], v[148:151], v[62:65]
	v_mfma_f32_16x16x32_bf16 v[58:61], v[192:195], v[148:151], v[58:61]
	v_mfma_f32_16x16x32_bf16 v[54:57], v[208:211], v[148:151], v[54:57]
	v_mfma_f32_16x16x32_bf16 v[50:53], v[212:215], v[148:151], v[50:53]
	v_mfma_f32_16x16x32_bf16 v[46:49], v[188:191], v[152:155], v[46:49]
	v_mfma_f32_16x16x32_bf16 v[42:45], v[192:195], v[152:155], v[42:45]
	v_mfma_f32_16x16x32_bf16 v[38:41], v[208:211], v[152:155], v[38:41]
	v_mfma_f32_16x16x32_bf16 v[34:37], v[212:215], v[152:155], v[34:37]
	v_mfma_f32_16x16x32_bf16 v[30:33], v[188:191], v[156:159], v[30:33]
	v_mfma_f32_16x16x32_bf16 v[26:29], v[192:195], v[156:159], v[26:29]
	v_mfma_f32_16x16x32_bf16 v[22:25], v[208:211], v[156:159], v[22:25]
	v_mfma_f32_16x16x32_bf16 v[18:21], v[212:215], v[156:159], v[18:21]
	v_mfma_f32_16x16x32_bf16 v[14:17], v[188:191], v[160:163], v[14:17]
	v_mfma_f32_16x16x32_bf16 v[10:13], v[192:195], v[160:163], v[10:13]
	v_mfma_f32_16x16x32_bf16 v[6:9], v[208:211], v[160:163], v[6:9]
	v_mfma_f32_16x16x32_bf16 v[2:5], v[212:215], v[160:163], v[2:5]
	v_mfma_f32_16x16x32_bf16 v[66:69], v[188:191], v[164:167], v[66:69]
	v_mfma_f32_16x16x32_bf16 v[70:73], v[192:195], v[164:167], v[70:73]
	v_mfma_f32_16x16x32_bf16 v[82:85], v[208:211], v[164:167], v[82:85]
	v_mfma_f32_16x16x32_bf16 v[88:91], v[212:215], v[164:167], v[88:91]
	v_mfma_f32_16x16x32_bf16 v[92:95], v[188:191], v[168:171], v[92:95]
	v_mfma_f32_16x16x32_bf16 v[96:99], v[192:195], v[168:171], v[96:99]
	v_mfma_f32_16x16x32_bf16 v[100:103], v[208:211], v[168:171], v[100:103]
	v_mfma_f32_16x16x32_bf16 v[106:109], v[212:215], v[168:171], v[106:109]
	v_mfma_f32_16x16x32_bf16 v[110:113], v[188:191], v[174:177], v[110:113]
	v_mfma_f32_16x16x32_bf16 v[114:117], v[192:195], v[174:177], v[114:117]
	v_mfma_f32_16x16x32_bf16 v[118:121], v[208:211], v[174:177], v[118:121]
	v_mfma_f32_16x16x32_bf16 v[122:125], v[212:215], v[174:177], v[122:125]
	v_mfma_f32_16x16x32_bf16 v[126:129], v[188:191], v[182:185], v[126:129]
	v_mfma_f32_16x16x32_bf16 v[136:139], v[192:195], v[182:185], v[136:139]
	v_mfma_f32_16x16x32_bf16 v[140:143], v[208:211], v[182:185], v[140:143]
	v_mfma_f32_16x16x32_bf16 v[144:147], v[212:215], v[182:185], v[144:147]
	s_setprio 0
	s_waitcnt vmcnt(0)
	s_barrier
	ds_read_b128 v[148:151], v78 offset:0
	ds_read_b128 v[152:155], v78 offset:2048
	ds_read_b128 v[156:159], v78 offset:4096
	ds_read_b128 v[160:163], v78 offset:6144
	ds_read_b128 v[188:191], v79 offset:49152
	ds_read_b128 v[192:195], v79 offset:51200
	ds_read_b128 v[208:211], v79 offset:53248
	ds_read_b128 v[212:215], v79 offset:55296
	ds_read_b128 v[164:167], v78 offset:16384
	ds_read_b128 v[168:171], v78 offset:18432
	ds_read_b128 v[174:177], v78 offset:20480
	ds_read_b128 v[182:185], v78 offset:22528
	s_setprio 1
	s_waitcnt lgkmcnt(4)
	v_mfma_f32_16x16x32_bf16 v[62:65], v[188:191], v[148:151], v[62:65]
	v_mfma_f32_16x16x32_bf16 v[58:61], v[192:195], v[148:151], v[58:61]
	v_mfma_f32_16x16x32_bf16 v[54:57], v[208:211], v[148:151], v[54:57]
	v_mfma_f32_16x16x32_bf16 v[50:53], v[212:215], v[148:151], v[50:53]
	v_mfma_f32_16x16x32_bf16 v[46:49], v[188:191], v[152:155], v[46:49]
	v_mfma_f32_16x16x32_bf16 v[42:45], v[192:195], v[152:155], v[42:45]
	v_mfma_f32_16x16x32_bf16 v[38:41], v[208:211], v[152:155], v[38:41]
	v_mfma_f32_16x16x32_bf16 v[34:37], v[212:215], v[152:155], v[34:37]
	v_mfma_f32_16x16x32_bf16 v[30:33], v[188:191], v[156:159], v[30:33]
	v_mfma_f32_16x16x32_bf16 v[26:29], v[192:195], v[156:159], v[26:29]
	v_mfma_f32_16x16x32_bf16 v[22:25], v[208:211], v[156:159], v[22:25]
	v_mfma_f32_16x16x32_bf16 v[18:21], v[212:215], v[156:159], v[18:21]
	v_mfma_f32_16x16x32_bf16 v[14:17], v[188:191], v[160:163], v[14:17]
	v_mfma_f32_16x16x32_bf16 v[10:13], v[192:195], v[160:163], v[10:13]
	v_mfma_f32_16x16x32_bf16 v[6:9], v[208:211], v[160:163], v[6:9]
	v_mfma_f32_16x16x32_bf16 v[2:5], v[212:215], v[160:163], v[2:5]
	s_waitcnt lgkmcnt(0)
	v_mfma_f32_16x16x32_bf16 v[66:69], v[188:191], v[164:167], v[66:69]
	v_mfma_f32_16x16x32_bf16 v[70:73], v[192:195], v[164:167], v[70:73]
	v_mfma_f32_16x16x32_bf16 v[82:85], v[208:211], v[164:167], v[82:85]
	v_mfma_f32_16x16x32_bf16 v[88:91], v[212:215], v[164:167], v[88:91]
	v_mfma_f32_16x16x32_bf16 v[92:95], v[188:191], v[168:171], v[92:95]
	v_mfma_f32_16x16x32_bf16 v[96:99], v[192:195], v[168:171], v[96:99]
	v_mfma_f32_16x16x32_bf16 v[100:103], v[208:211], v[168:171], v[100:103]
	v_mfma_f32_16x16x32_bf16 v[106:109], v[212:215], v[168:171], v[106:109]
	v_mfma_f32_16x16x32_bf16 v[110:113], v[188:191], v[174:177], v[110:113]
	v_mfma_f32_16x16x32_bf16 v[114:117], v[192:195], v[174:177], v[114:117]
	v_mfma_f32_16x16x32_bf16 v[118:121], v[208:211], v[174:177], v[118:121]
	v_mfma_f32_16x16x32_bf16 v[122:125], v[212:215], v[174:177], v[122:125]
	v_mfma_f32_16x16x32_bf16 v[126:129], v[188:191], v[182:185], v[126:129]
	v_mfma_f32_16x16x32_bf16 v[136:139], v[192:195], v[182:185], v[136:139]
	v_mfma_f32_16x16x32_bf16 v[140:143], v[208:211], v[182:185], v[140:143]
	v_mfma_f32_16x16x32_bf16 v[144:147], v[212:215], v[182:185], v[144:147]
	s_setprio 0
	ds_read_b128 v[148:151], v80 offset:0
	ds_read_b128 v[152:155], v80 offset:2048
	ds_read_b128 v[156:159], v80 offset:4096
	ds_read_b128 v[160:163], v80 offset:6144
	ds_read_b128 v[188:191], v81 offset:49152
	ds_read_b128 v[192:195], v81 offset:51200
	ds_read_b128 v[208:211], v81 offset:53248
	ds_read_b128 v[212:215], v81 offset:55296
	ds_read_b128 v[164:167], v80 offset:16384
	ds_read_b128 v[168:171], v80 offset:18432
	ds_read_b128 v[174:177], v80 offset:20480
	ds_read_b128 v[182:185], v80 offset:22528
	s_setprio 1
	s_waitcnt lgkmcnt(4)
	v_mfma_f32_16x16x32_bf16 v[62:65], v[188:191], v[148:151], v[62:65]
	v_mfma_f32_16x16x32_bf16 v[58:61], v[192:195], v[148:151], v[58:61]
	v_mfma_f32_16x16x32_bf16 v[54:57], v[208:211], v[148:151], v[54:57]
	v_mfma_f32_16x16x32_bf16 v[50:53], v[212:215], v[148:151], v[50:53]
	v_mfma_f32_16x16x32_bf16 v[46:49], v[188:191], v[152:155], v[46:49]
	v_mfma_f32_16x16x32_bf16 v[42:45], v[192:195], v[152:155], v[42:45]
	v_mfma_f32_16x16x32_bf16 v[38:41], v[208:211], v[152:155], v[38:41]
	v_mfma_f32_16x16x32_bf16 v[34:37], v[212:215], v[152:155], v[34:37]
	v_mfma_f32_16x16x32_bf16 v[30:33], v[188:191], v[156:159], v[30:33]
	v_mfma_f32_16x16x32_bf16 v[26:29], v[192:195], v[156:159], v[26:29]
	v_mfma_f32_16x16x32_bf16 v[22:25], v[208:211], v[156:159], v[22:25]
	v_mfma_f32_16x16x32_bf16 v[18:21], v[212:215], v[156:159], v[18:21]
	v_mfma_f32_16x16x32_bf16 v[14:17], v[188:191], v[160:163], v[14:17]
	v_mfma_f32_16x16x32_bf16 v[10:13], v[192:195], v[160:163], v[10:13]
	v_mfma_f32_16x16x32_bf16 v[6:9], v[208:211], v[160:163], v[6:9]
	v_mfma_f32_16x16x32_bf16 v[2:5], v[212:215], v[160:163], v[2:5]
	s_waitcnt lgkmcnt(0)
	v_mfma_f32_16x16x32_bf16 v[66:69], v[188:191], v[164:167], v[66:69]
	v_mfma_f32_16x16x32_bf16 v[70:73], v[192:195], v[164:167], v[70:73]
	v_mfma_f32_16x16x32_bf16 v[82:85], v[208:211], v[164:167], v[82:85]
	v_mfma_f32_16x16x32_bf16 v[88:91], v[212:215], v[164:167], v[88:91]
	v_mfma_f32_16x16x32_bf16 v[92:95], v[188:191], v[168:171], v[92:95]
	v_mfma_f32_16x16x32_bf16 v[96:99], v[192:195], v[168:171], v[96:99]
	v_mfma_f32_16x16x32_bf16 v[100:103], v[208:211], v[168:171], v[100:103]
	v_mfma_f32_16x16x32_bf16 v[106:109], v[212:215], v[168:171], v[106:109]
	v_mfma_f32_16x16x32_bf16 v[110:113], v[188:191], v[174:177], v[110:113]
	v_mfma_f32_16x16x32_bf16 v[114:117], v[192:195], v[174:177], v[114:117]
	v_mfma_f32_16x16x32_bf16 v[118:121], v[208:211], v[174:177], v[118:121]
	v_mfma_f32_16x16x32_bf16 v[122:125], v[212:215], v[174:177], v[122:125]
	v_mfma_f32_16x16x32_bf16 v[126:129], v[188:191], v[182:185], v[126:129]
	v_mfma_f32_16x16x32_bf16 v[136:139], v[192:195], v[182:185], v[136:139]
	v_mfma_f32_16x16x32_bf16 v[140:143], v[208:211], v[182:185], v[140:143]
	v_mfma_f32_16x16x32_bf16 v[144:147], v[212:215], v[182:185], v[144:147]
	s_setprio 0
	s_nop 7
	s_nop 7
	s_nop 7
	v_mov_b32_e32 v148, v66
	v_mov_b32_e32 v149, v67
	v_mov_b32_e32 v150, v68
	v_mov_b32_e32 v151, v69
	v_mov_b32_e32 v152, v70
	v_mov_b32_e32 v153, v71
	v_mov_b32_e32 v154, v72
	v_mov_b32_e32 v155, v73
	v_mov_b32_e32 v156, v82
	v_mov_b32_e32 v157, v83
	v_mov_b32_e32 v158, v84
	v_mov_b32_e32 v159, v85
	v_mov_b32_e32 v160, v88
	v_mov_b32_e32 v161, v89
	v_mov_b32_e32 v162, v90
	v_mov_b32_e32 v163, v91
	v_mov_b32_e32 v164, v92
	v_mov_b32_e32 v165, v93
	v_mov_b32_e32 v166, v94
	v_mov_b32_e32 v167, v95
	v_mov_b32_e32 v168, v96
	v_mov_b32_e32 v169, v97
	v_mov_b32_e32 v170, v98
	v_mov_b32_e32 v171, v99
	v_mov_b32_e32 v174, v100
	v_mov_b32_e32 v175, v101
	v_mov_b32_e32 v176, v102
	v_mov_b32_e32 v177, v103
	v_mov_b32_e32 v182, v106
	v_mov_b32_e32 v183, v107
	v_mov_b32_e32 v184, v108
	v_mov_b32_e32 v185, v109
	v_mov_b32_e32 v188, v110
	v_mov_b32_e32 v189, v111
	v_mov_b32_e32 v190, v112
	v_mov_b32_e32 v191, v113
	v_mov_b32_e32 v192, v114
	v_mov_b32_e32 v193, v115
	v_mov_b32_e32 v194, v116
	v_mov_b32_e32 v195, v117
	v_mov_b32_e32 v208, v118
	v_mov_b32_e32 v209, v119
	v_mov_b32_e32 v210, v120
	v_mov_b32_e32 v211, v121
	v_mov_b32_e32 v212, v122
	v_mov_b32_e32 v213, v123
	v_mov_b32_e32 v214, v124
	v_mov_b32_e32 v215, v125
	v_mov_b32_e32 v216, v126
	v_mov_b32_e32 v217, v127
	v_mov_b32_e32 v218, v128
	v_mov_b32_e32 v219, v129
	v_mov_b32_e32 v220, v136
	v_mov_b32_e32 v221, v137
	v_mov_b32_e32 v222, v138
	v_mov_b32_e32 v223, v139
	v_mov_b32_e32 v242, v140
	v_mov_b32_e32 v243, v141
	v_mov_b32_e32 v244, v142
	v_mov_b32_e32 v245, v143
	v_mov_b32_e32 v199, v144
	v_mov_b32_e32 v206, v145
	v_mov_b32_e32 v207, v146
	v_mov_b32_e32 v226, v147
	s_add_i32 s48, s48, 1
	s_mov_b32 s65, 0
	v_readlane_b32 s2, v249, 0
	s_nop 0
	s_and_b32 s3, s2, 7
	s_lshr_b32 s2, s2, 3
	s_cmp_lt_u32 s2, 40
	s_cselect_b32 s38, 7, 6
	s_cmp_lt_u32 s48, s38
	s_cbranch_scc0 .Lg2_c1_extra
	s_lshl_b32 s20, s48, 6
	s_add_i32 s20, s20, s2
	s_cmp_ge_u32 s20, 0xd4
	s_cselect_b32 s21, 1, 0
	s_mul_i32 s60, s21, 0xd4
	s_sub_i32 s20, s20, s60
	s_lshr_b32 s61, s20, 2
	s_and_b32 s20, s20, 3
	s_lshl_b32 s21, s21, 3
	s_add_i32 s20, s20, s21
	s_lshl_b32 s20, s20, 3
	s_add_i32 s60, s20, s3
	s_add_i32 s64, s60, 32
	s_branch .Lg2_c1_have

.LBB0_567:
	s_or_b64 exec, exec, s[4:5]
	v_or_b32_e32 v0, 56, v23
	v_mul_u32_u24_e32 v0, 0x88, v0
	v_lshlrev_b32_e32 v0, 1, v0
	v_cvt_pk_bf16_f32 v6, v6, v7
	v_add_u32_e32 v7, v26, v0
	v_lshl_add_u32 v0, v19, 1, v0
	ds_write_b16 v7, v6
	ds_write_b16_d16_hi v0, v6 offset:272
	v_cvt_pk_bf16_f32 v0, v8, v9
	ds_write_b16 v24, v0 offset:15776
	ds_write_b16_d16_hi v25, v0 offset:16048
	v_cvt_pk_bf16_f32 v0, v2, v3
	v_readlane_b32 s0, v250, 12
	ds_write_b16 v24, v0 offset:16320
	ds_write_b16_d16_hi v25, v0 offset:16592
	v_cvt_pk_bf16_f32 v0, v4, v5
	v_readlane_b32 s1, v250, 13
	ds_write_b16 v24, v0 offset:16864
	ds_write_b16_d16_hi v25, v0 offset:17136
	s_waitcnt lgkmcnt(0)
	s_barrier
	s_load_dwordx2 s[2:3], s[0:1], 0x128
	v_readlane_b32 s0, v250, 21
	s_or_b32 s0, s9, s0
	s_waitcnt vmcnt(3)
	v_and_b32_e32 v68, 15, v22
	s_lshl_b32 s1, s0, 15
	v_ashrrev_i32_e32 v66, 6, v22
	v_bfe_u32 v67, v22, 4, 2
	s_waitcnt lgkmcnt(0)
	s_add_u32 s2, s2, s1
	v_lshlrev_b32_e32 v2, 7, v68
	s_addc_u32 s3, s3, 0
	v_lshlrev_b32_e32 v0, 4, v67
	v_lshl_or_b32 v10, v66, 12, v2
	v_lshl_add_u64 v[4:5], s[2:3], 0, v[0:1]
	v_ashrrev_i32_e32 v11, 31, v10
	v_lshl_add_u64 v[2:3], v[10:11], 1, v[4:5]
	v_or_b32_e32 v10, 0x800, v10
	v_ashrrev_i32_e32 v11, 31, v10
	v_lshl_add_u64 v[4:5], v[10:11], 1, v[4:5]
	global_load_dwordx4 v[6:9], v[2:3], off
	global_load_dwordx4 v[10:13], v[4:5], off
	s_movk_i32 s1, 0x110
	v_mad_u32_u24 v0, v68, s1, v0
	ds_read_b128 v[14:17], v0
	ds_read_b128 v[22:25], v0 offset:4352
	ds_read_b128 v[30:33], v0 offset:8704
	ds_read_b128 v[38:41], v0 offset:13056
	ds_read_b128 v[46:49], v0 offset:17408
	ds_read_b128 v[54:57], v0 offset:21760
	ds_read_b128 v[62:65], v0 offset:26112
	s_waitcnt vmcnt(4)
	ds_read_b128 v[74:77], v0 offset:30464
	v_lshl_or_b32 v66, v66, 5, v68
	s_lshl_b32 s0, s0, 7
	v_cmp_gt_i32_e32 vcc, s7, v66
	s_waitcnt vmcnt(1) lgkmcnt(7)
	v_mfma_f32_16x16x32_bf16 v[18:21], v[14:17], v[6:9], 0
	s_waitcnt vmcnt(0)
	v_mfma_f32_16x16x32_bf16 v[14:17], v[14:17], v[10:13], 0
	s_waitcnt lgkmcnt(6)
	v_mfma_f32_16x16x32_bf16 v[26:29], v[22:25], v[6:9], 0
	v_mfma_f32_16x16x32_bf16 v[22:25], v[22:25], v[10:13], 0
	s_waitcnt lgkmcnt(5)
	v_mfma_f32_16x16x32_bf16 v[34:37], v[30:33], v[6:9], 0
	v_mfma_f32_16x16x32_bf16 v[30:33], v[30:33], v[10:13], 0
	s_waitcnt lgkmcnt(4)
	v_mfma_f32_16x16x32_bf16 v[42:45], v[38:41], v[6:9], 0
	v_mfma_f32_16x16x32_bf16 v[38:41], v[38:41], v[10:13], 0
	s_waitcnt lgkmcnt(3)
	v_mfma_f32_16x16x32_bf16 v[50:53], v[46:49], v[6:9], 0
	v_mfma_f32_16x16x32_bf16 v[46:49], v[46:49], v[10:13], 0
	s_waitcnt lgkmcnt(2)
	v_mfma_f32_16x16x32_bf16 v[58:61], v[54:57], v[6:9], 0
	v_mfma_f32_16x16x32_bf16 v[54:57], v[54:57], v[10:13], 0
	s_waitcnt lgkmcnt(1)
	v_mfma_f32_16x16x32_bf16 v[70:73], v[62:65], v[6:9], 0
	v_mfma_f32_16x16x32_bf16 v[62:65], v[62:65], v[10:13], 0
	s_waitcnt lgkmcnt(0)
	v_mfma_f32_16x16x32_bf16 v[6:9], v[74:77], v[6:9], 0
	v_mfma_f32_16x16x32_bf16 v[10:13], v[74:77], v[10:13], 0
	global_load_dwordx4 v[74:77], v[2:3], off offset:64
	global_load_dwordx4 v[78:81], v[4:5], off offset:64
	ds_read_b128 v[82:85], v0 offset:64
	s_waitcnt vmcnt(1) lgkmcnt(0)
	v_mfma_f32_16x16x32_bf16 v[18:21], v[82:85], v[74:77], v[18:21]
	s_waitcnt vmcnt(0)
	v_mfma_f32_16x16x32_bf16 v[14:17], v[82:85], v[78:81], v[14:17]
	ds_read_b128 v[82:85], v0 offset:4416
	s_waitcnt lgkmcnt(0)
	v_mfma_f32_16x16x32_bf16 v[26:29], v[82:85], v[74:77], v[26:29]
	v_mfma_f32_16x16x32_bf16 v[22:25], v[82:85], v[78:81], v[22:25]
	ds_read_b128 v[82:85], v0 offset:8768
	s_waitcnt lgkmcnt(0)
	v_mfma_f32_16x16x32_bf16 v[34:37], v[82:85], v[74:77], v[34:37]
	v_mfma_f32_16x16x32_bf16 v[30:33], v[82:85], v[78:81], v[30:33]
	ds_read_b128 v[82:85], v0 offset:13120
	s_waitcnt lgkmcnt(0)
	v_mfma_f32_16x16x32_bf16 v[42:45], v[82:85], v[74:77], v[42:45]
	v_mfma_f32_16x16x32_bf16 v[38:41], v[82:85], v[78:81], v[38:41]
	ds_read_b128 v[82:85], v0 offset:17472
	s_waitcnt lgkmcnt(0)
	v_mfma_f32_16x16x32_bf16 v[50:53], v[82:85], v[74:77], v[50:53]
	v_mfma_f32_16x16x32_bf16 v[46:49], v[82:85], v[78:81], v[46:49]
	ds_read_b128 v[82:85], v0 offset:21824
	s_waitcnt lgkmcnt(0)
	v_mfma_f32_16x16x32_bf16 v[58:61], v[82:85], v[74:77], v[58:61]
	v_mfma_f32_16x16x32_bf16 v[54:57], v[82:85], v[78:81], v[54:57]
	ds_read_b128 v[82:85], v0 offset:26176
	s_waitcnt lgkmcnt(0)
	v_mfma_f32_16x16x32_bf16 v[70:73], v[82:85], v[74:77], v[70:73]
	v_mfma_f32_16x16x32_bf16 v[62:65], v[82:85], v[78:81], v[62:65]
	ds_read_b128 v[82:85], v0 offset:30528
	s_waitcnt lgkmcnt(0)
	v_mfma_f32_16x16x32_bf16 v[6:9], v[82:85], v[74:77], v[6:9]
	v_mfma_f32_16x16x32_bf16 v[10:13], v[82:85], v[78:81], v[10:13]
	global_load_dwordx4 v[74:77], v[2:3], off offset:128
	global_load_dwordx4 v[78:81], v[4:5], off offset:128
	ds_read_b128 v[82:85], v0 offset:128
	s_waitcnt vmcnt(1) lgkmcnt(0)
	v_mfma_f32_16x16x32_bf16 v[18:21], v[82:85], v[74:77], v[18:21]
	s_waitcnt vmcnt(0)
	v_mfma_f32_16x16x32_bf16 v[14:17], v[82:85], v[78:81], v[14:17]
	ds_read_b128 v[82:85], v0 offset:4480
	s_waitcnt lgkmcnt(0)
	v_mfma_f32_16x16x32_bf16 v[26:29], v[82:85], v[74:77], v[26:29]
	v_mfma_f32_16x16x32_bf16 v[22:25], v[82:85], v[78:81], v[22:25]
	ds_read_b128 v[82:85], v0 offset:8832
	s_waitcnt lgkmcnt(0)
	v_mfma_f32_16x16x32_bf16 v[34:37], v[82:85], v[74:77], v[34:37]
	v_mfma_f32_16x16x32_bf16 v[82:85], v[82:85], v[78:81], v[30:33]
	s_nop 2
	ds_read_b128 v[30:33], v0 offset:13184
	s_waitcnt lgkmcnt(0)
	v_mfma_f32_16x16x32_bf16 v[42:45], v[30:33], v[74:77], v[42:45]
	v_mfma_f32_16x16x32_bf16 v[38:41], v[30:33], v[78:81], v[38:41]
	ds_read_b128 v[30:33], v0 offset:17536
	s_waitcnt lgkmcnt(0)
	v_mfma_f32_16x16x32_bf16 v[86:89], v[30:33], v[74:77], v[50:53]
	v_mfma_f32_16x16x32_bf16 v[90:93], v[30:33], v[78:81], v[46:49]
	ds_read_b128 v[30:33], v0 offset:21888
	s_waitcnt lgkmcnt(0)
	v_mfma_f32_16x16x32_bf16 v[94:97], v[30:33], v[74:77], v[58:61]
	v_mfma_f32_16x16x32_bf16 v[98:101], v[30:33], v[78:81], v[54:57]
	ds_read_b128 v[30:33], v0 offset:26240
	s_waitcnt lgkmcnt(0)
	v_mfma_f32_16x16x32_bf16 v[70:73], v[30:33], v[74:77], v[70:73]
	v_mfma_f32_16x16x32_bf16 v[102:105], v[30:33], v[78:81], v[62:65]
	ds_read_b128 v[30:33], v0 offset:30592
	global_load_dwordx4 v[106:109], v[2:3], off offset:192
	s_nop 0
	global_load_dwordx4 v[2:5], v[4:5], off offset:192
	s_waitcnt lgkmcnt(0)
	v_mfma_f32_16x16x32_bf16 v[74:77], v[30:33], v[74:77], v[6:9]
	s_nop 2
	ds_read_b128 v[6:9], v0 offset:192
	v_mfma_f32_16x16x32_bf16 v[78:81], v[30:33], v[78:81], v[10:13]
	s_waitcnt vmcnt(1) lgkmcnt(0)
	v_mfma_f32_16x16x32_bf16 v[62:65], v[6:9], v[106:109], v[18:21]
	s_waitcnt vmcnt(0)
	v_mfma_f32_16x16x32_bf16 v[30:33], v[6:9], v[2:5], v[14:17]
	ds_read_b128 v[6:9], v0 offset:4544
	s_waitcnt lgkmcnt(0)
	v_mfma_f32_16x16x32_bf16 v[58:61], v[6:9], v[106:109], v[26:29]
	v_mfma_f32_16x16x32_bf16 v[26:29], v[6:9], v[2:5], v[22:25]
	ds_read_b128 v[6:9], v0 offset:8896
	s_waitcnt lgkmcnt(0)
	v_mfma_f32_16x16x32_bf16 v[54:57], v[6:9], v[106:109], v[34:37]
	v_mfma_f32_16x16x32_bf16 v[22:25], v[6:9], v[2:5], v[82:85]
	ds_read_b128 v[6:9], v0 offset:13248
	s_waitcnt lgkmcnt(0)
	v_mfma_f32_16x16x32_bf16 v[50:53], v[6:9], v[106:109], v[42:45]
	v_mfma_f32_16x16x32_bf16 v[18:21], v[6:9], v[2:5], v[38:41]
	ds_read_b128 v[6:9], v0 offset:17600
	s_waitcnt lgkmcnt(0)
	v_mfma_f32_16x16x32_bf16 v[46:49], v[6:9], v[106:109], v[86:89]
	v_mfma_f32_16x16x32_bf16 v[14:17], v[6:9], v[2:5], v[90:93]
	ds_read_b128 v[6:9], v0 offset:21952
	s_waitcnt lgkmcnt(0)
	v_mfma_f32_16x16x32_bf16 v[42:45], v[6:9], v[106:109], v[94:97]
	v_mfma_f32_16x16x32_bf16 v[10:13], v[6:9], v[2:5], v[98:101]
	ds_read_b128 v[6:9], v0 offset:26304
	s_waitcnt lgkmcnt(0)
	v_mfma_f32_16x16x32_bf16 v[38:41], v[6:9], v[106:109], v[70:73]
	s_nop 2
	ds_read_b128 v[70:73], v0 offset:30656
	v_lshlrev_b32_e32 v0, 2, v67
	v_lshlrev_b32_e32 v0, 1, v0
	v_mfma_f32_16x16x32_bf16 v[6:9], v[6:9], v[2:5], v[102:105]
	s_waitcnt lgkmcnt(0)
	v_mfma_f32_16x16x32_bf16 v[34:37], v[70:73], v[106:109], v[74:77]
	v_mfma_f32_16x16x32_bf16 v[2:5], v[70:73], v[2:5], v[78:81]
	s_and_saveexec_b64 s[2:3], vcc
	s_cbranch_execz .LBB0_569
	v_readlane_b32 s10, v250, 12
	v_readlane_b32 s11, v250, 13
	s_load_dwordx2 s[4:5], s[10:11], 0x70
	v_add_u32_e32 v68, s0, v66
	v_ashrrev_i32_e32 v69, 31, v68
	v_add_u32_e32 v70, s6, v66
	v_ashrrev_i32_e32 v71, 31, v70
	s_waitcnt lgkmcnt(0)
	v_lshl_add_u64 v[68:69], v[68:69], 2, s[4:5]
	s_load_dwordx2 s[4:5], s[10:11], 0x140
	v_lshlrev_b64 v[70:71], 10, v[70:71]
	s_lshl_b32 s72, s8, 1
	global_load_dword v68, v[68:69], off
	s_waitcnt lgkmcnt(0)
	v_lshl_add_u64 v[72:73], s[4:5], 0, v[70:71]
	s_load_dwordx2 s[4:5], s[10:11], 0x1a0
	v_lshl_add_u64 v[72:73], v[72:73], 0, s[72:73]
	s_waitcnt lgkmcnt(0)
	v_lshl_add_u64 v[70:71], s[4:5], 0, v[70:71]
	v_lshl_add_u64 v[74:75], v[70:71], 0, s[72:73]
	v_lshl_add_u64 v[70:71], v[72:73], 0, v[0:1]
	global_load_dwordx2 v[72:73], v[70:71], off
	global_load_dwordx2 v[148:149], v[70:71], off offset:32
	global_load_dwordx2 v[150:151], v[70:71], off offset:64
	global_load_dwordx2 v[152:153], v[70:71], off offset:96
	global_load_dwordx2 v[154:155], v[70:71], off offset:128
	global_load_dwordx2 v[156:157], v[70:71], off offset:160
	global_load_dwordx2 v[158:159], v[70:71], off offset:192
	global_load_dwordx2 v[160:161], v[70:71], off offset:224
	s_waitcnt vmcnt(1)
	v_pk_add_f32 v[62:63], v[62:63], v[68:69] op_sel_hi:[1,0]
	v_pk_add_f32 v[64:65], v[64:65], v[68:69] op_sel_hi:[1,0]
	v_pk_add_f32 v[58:59], v[58:59], v[68:69] op_sel_hi:[1,0]
	v_pk_add_f32 v[60:61], v[60:61], v[68:69] op_sel_hi:[1,0]
	v_pk_add_f32 v[54:55], v[54:55], v[68:69] op_sel_hi:[1,0]
	v_pk_add_f32 v[56:57], v[56:57], v[68:69] op_sel_hi:[1,0]
	v_pk_add_f32 v[50:51], v[50:51], v[68:69] op_sel_hi:[1,0]
	v_pk_add_f32 v[52:53], v[52:53], v[68:69] op_sel_hi:[1,0]
	v_pk_add_f32 v[46:47], v[46:47], v[68:69] op_sel_hi:[1,0]
	v_pk_add_f32 v[48:49], v[48:49], v[68:69] op_sel_hi:[1,0]
	v_pk_add_f32 v[42:43], v[42:43], v[68:69] op_sel_hi:[1,0]
	s_waitcnt vmcnt(0)
	v_lshlrev_b32_e32 v76, 16, v72
	v_and_b32_e32 v77, 0xffff0000, v72
	v_pk_mul_f32 v[76:77], v[62:63], v[76:77]
	v_lshlrev_b32_e32 v62, 16, v73
	v_and_b32_e32 v63, 0xffff0000, v73
	v_pk_mul_f32 v[64:65], v[64:65], v[62:63]
	v_lshl_add_u64 v[62:63], v[74:75], 0, v[0:1]
	v_cvt_pk_bf16_f32 v72, v76, v77
	v_cvt_pk_bf16_f32 v73, v64, v65
	global_store_dwordx2 v[62:63], v[72:73], off
	s_nop 3
	v_mov_b32_e32 v64, v148
	v_mov_b32_e32 v65, v149
	v_pk_add_f32 v[44:45], v[44:45], v[68:69] op_sel_hi:[1,0]
	v_pk_add_f32 v[38:39], v[38:39], v[68:69] op_sel_hi:[1,0]
	v_pk_add_f32 v[40:41], v[40:41], v[68:69] op_sel_hi:[1,0]
	v_pk_add_f32 v[34:35], v[34:35], v[68:69] op_sel_hi:[1,0]
	v_pk_add_f32 v[36:37], v[36:37], v[68:69] op_sel_hi:[1,0]
	v_lshlrev_b32_e32 v72, 16, v64
	v_and_b32_e32 v73, 0xffff0000, v64
	v_lshlrev_b32_e32 v64, 16, v65
	v_and_b32_e32 v65, 0xffff0000, v65
	v_pk_mul_f32 v[58:59], v[58:59], v[72:73]
	v_pk_mul_f32 v[60:61], v[60:61], v[64:65]
	v_cvt_pk_bf16_f32 v58, v58, v59
	v_cvt_pk_bf16_f32 v59, v60, v61
	global_store_dwordx2 v[62:63], v[58:59], off offset:32
	s_nop 3
	v_mov_b32_e32 v58, v150
	v_mov_b32_e32 v59, v151
	v_lshlrev_b32_e32 v60, 16, v58
	v_and_b32_e32 v61, 0xffff0000, v58
	v_lshlrev_b32_e32 v58, 16, v59
	v_and_b32_e32 v59, 0xffff0000, v59
	v_pk_mul_f32 v[54:55], v[54:55], v[60:61]
	v_pk_mul_f32 v[56:57], v[56:57], v[58:59]
	v_cvt_pk_bf16_f32 v54, v54, v55
	v_cvt_pk_bf16_f32 v55, v56, v57
	global_store_dwordx2 v[62:63], v[54:55], off offset:64
	s_nop 3
	v_mov_b32_e32 v54, v152
	v_mov_b32_e32 v55, v153
	v_lshlrev_b32_e32 v56, 16, v54
	v_and_b32_e32 v57, 0xffff0000, v54
	v_lshlrev_b32_e32 v54, 16, v55
	v_and_b32_e32 v55, 0xffff0000, v55
	v_pk_mul_f32 v[50:51], v[50:51], v[56:57]
	v_pk_mul_f32 v[52:53], v[52:53], v[54:55]
	v_cvt_pk_bf16_f32 v50, v50, v51
	v_cvt_pk_bf16_f32 v51, v52, v53
	global_store_dwordx2 v[62:63], v[50:51], off offset:96
	s_nop 3
	v_mov_b32_e32 v50, v154
	v_mov_b32_e32 v51, v155
	v_lshlrev_b32_e32 v52, 16, v50
	v_and_b32_e32 v53, 0xffff0000, v50
	v_lshlrev_b32_e32 v50, 16, v51
	v_and_b32_e32 v51, 0xffff0000, v51
	v_pk_mul_f32 v[46:47], v[46:47], v[52:53]
	v_pk_mul_f32 v[48:49], v[48:49], v[50:51]
	v_cvt_pk_bf16_f32 v46, v46, v47
	v_cvt_pk_bf16_f32 v47, v48, v49
	global_store_dwordx2 v[62:63], v[46:47], off offset:128
	s_nop 3
	v_mov_b32_e32 v46, v156
	v_mov_b32_e32 v47, v157
	v_lshlrev_b32_e32 v48, 16, v46
	v_and_b32_e32 v49, 0xffff0000, v46
	v_lshlrev_b32_e32 v46, 16, v47
	v_and_b32_e32 v47, 0xffff0000, v47
	v_pk_mul_f32 v[42:43], v[42:43], v[48:49]
	v_pk_mul_f32 v[44:45], v[44:45], v[46:47]
	v_cvt_pk_bf16_f32 v42, v42, v43
	v_cvt_pk_bf16_f32 v43, v44, v45
	global_store_dwordx2 v[62:63], v[42:43], off offset:160
	s_nop 3
	v_mov_b32_e32 v42, v158
	v_mov_b32_e32 v43, v159
	v_lshlrev_b32_e32 v44, 16, v42
	v_and_b32_e32 v45, 0xffff0000, v42
	v_lshlrev_b32_e32 v42, 16, v43
	v_and_b32_e32 v43, 0xffff0000, v43
	v_pk_mul_f32 v[38:39], v[38:39], v[44:45]
	v_pk_mul_f32 v[40:41], v[40:41], v[42:43]
	v_cvt_pk_bf16_f32 v38, v38, v39
	v_cvt_pk_bf16_f32 v39, v40, v41
	global_store_dwordx2 v[62:63], v[38:39], off offset:192
	s_nop 3
	v_mov_b32_e32 v38, v160
	v_mov_b32_e32 v39, v161
	v_lshlrev_b32_e32 v40, 16, v38
	v_and_b32_e32 v41, 0xffff0000, v38
	v_lshlrev_b32_e32 v38, 16, v39
	v_and_b32_e32 v39, 0xffff0000, v39
	v_pk_mul_f32 v[34:35], v[34:35], v[40:41]
	v_pk_mul_f32 v[36:37], v[36:37], v[38:39]
	v_cvt_pk_bf16_f32 v34, v34, v35
	v_cvt_pk_bf16_f32 v35, v36, v37
	global_store_dwordx2 v[62:63], v[34:35], off offset:224
.LBB0_569:
	s_or_b64 exec, exec, s[2:3]
	s_nop 3
	v_or_b32_e32 v34, 16, v66
	v_cmp_gt_i32_e32 vcc, s7, v34
	s_and_saveexec_b64 s[2:3], vcc
	s_cbranch_execz .LBB0_571
	v_add_u32_e32 v36, s6, v34
	v_readlane_b32 s6, v250, 12
	v_readlane_b32 s7, v250, 13
	s_mov_b32 s1, s73
	v_ashrrev_i32_e32 v67, 31, v66
	s_load_dwordx2 s[4:5], s[6:7], 0x70
	v_lshl_add_u64 v[34:35], v[66:67], 0, s[0:1]
	s_load_dwordx2 s[0:1], s[6:7], 0x140
	v_ashrrev_i32_e32 v37, 31, v36
	v_lshlrev_b64 v[38:39], 10, v[36:37]
	s_lshl_b32 s72, s8, 1
	s_waitcnt lgkmcnt(0)
	v_lshl_add_u64 v[34:35], v[34:35], 2, s[4:5]
	v_lshl_add_u64 v[36:37], s[0:1], 0, v[38:39]
	v_lshl_add_u64 v[36:37], v[36:37], 0, s[72:73]
	v_lshl_add_u64 v[36:37], v[36:37], 0, v[0:1]
	global_load_dword v34, v[34:35], off offset:64
	s_load_dwordx2 s[0:1], s[6:7], 0x1a0
	global_load_dwordx2 v[40:41], v[36:37], off
	global_load_dwordx2 v[148:149], v[36:37], off offset:32
	global_load_dwordx2 v[150:151], v[36:37], off offset:64
	global_load_dwordx2 v[152:153], v[36:37], off offset:96
	global_load_dwordx2 v[154:155], v[36:37], off offset:128
	global_load_dwordx2 v[156:157], v[36:37], off offset:160
	global_load_dwordx2 v[158:159], v[36:37], off offset:192
	global_load_dwordx2 v[160:161], v[36:37], off offset:224
	s_waitcnt lgkmcnt(0)
	v_lshl_add_u64 v[38:39], s[0:1], 0, v[38:39]
	v_lshl_add_u64 v[38:39], v[38:39], 0, s[72:73]
	v_lshl_add_u64 v[38:39], v[38:39], 0, v[0:1]
	s_waitcnt vmcnt(1)
	v_pk_add_f32 v[30:31], v[30:31], v[34:35] op_sel_hi:[1,0]
	v_pk_add_f32 v[32:33], v[32:33], v[34:35] op_sel_hi:[1,0]
	s_waitcnt vmcnt(0)
	v_lshlrev_b32_e32 v42, 16, v40
	v_and_b32_e32 v43, 0xffff0000, v40
	v_lshlrev_b32_e32 v40, 16, v41
	v_and_b32_e32 v41, 0xffff0000, v41
	v_pk_mul_f32 v[30:31], v[30:31], v[42:43]
	v_pk_mul_f32 v[32:33], v[32:33], v[40:41]
	v_cvt_pk_bf16_f32 v30, v30, v31
	v_cvt_pk_bf16_f32 v31, v32, v33
	global_store_dwordx2 v[38:39], v[30:31], off
	s_nop 3
	v_mov_b32_e32 v30, v148
	v_mov_b32_e32 v31, v149
	v_pk_add_f32 v[26:27], v[26:27], v[34:35] op_sel_hi:[1,0]
	v_pk_add_f32 v[28:29], v[28:29], v[34:35] op_sel_hi:[1,0]
	v_pk_add_f32 v[22:23], v[22:23], v[34:35] op_sel_hi:[1,0]
	v_pk_add_f32 v[24:25], v[24:25], v[34:35] op_sel_hi:[1,0]
	v_pk_add_f32 v[18:19], v[18:19], v[34:35] op_sel_hi:[1,0]
	v_pk_add_f32 v[20:21], v[20:21], v[34:35] op_sel_hi:[1,0]
	v_pk_add_f32 v[14:15], v[14:15], v[34:35] op_sel_hi:[1,0]
	v_pk_add_f32 v[16:17], v[16:17], v[34:35] op_sel_hi:[1,0]
	v_pk_add_f32 v[10:11], v[10:11], v[34:35] op_sel_hi:[1,0]
	v_pk_add_f32 v[12:13], v[12:13], v[34:35] op_sel_hi:[1,0]
	v_pk_add_f32 v[6:7], v[6:7], v[34:35] op_sel_hi:[1,0]
	v_pk_add_f32 v[8:9], v[8:9], v[34:35] op_sel_hi:[1,0]
	v_pk_add_f32 v[2:3], v[2:3], v[34:35] op_sel_hi:[1,0]
	v_pk_add_f32 v[4:5], v[4:5], v[34:35] op_sel_hi:[1,0]
	v_lshlrev_b32_e32 v32, 16, v30
	v_and_b32_e32 v33, 0xffff0000, v30
	v_lshlrev_b32_e32 v30, 16, v31
	v_and_b32_e32 v31, 0xffff0000, v31
	v_pk_mul_f32 v[26:27], v[26:27], v[32:33]
	v_pk_mul_f32 v[28:29], v[28:29], v[30:31]
	v_cvt_pk_bf16_f32 v26, v26, v27
	v_cvt_pk_bf16_f32 v27, v28, v29
	global_store_dwordx2 v[38:39], v[26:27], off offset:32
	s_nop 3
	v_mov_b32_e32 v26, v150
	v_mov_b32_e32 v27, v151
	v_lshlrev_b32_e32 v28, 16, v26
	v_and_b32_e32 v29, 0xffff0000, v26
	v_lshlrev_b32_e32 v26, 16, v27
	v_and_b32_e32 v27, 0xffff0000, v27
	v_pk_mul_f32 v[22:23], v[22:23], v[28:29]
	v_pk_mul_f32 v[24:25], v[24:25], v[26:27]
	v_cvt_pk_bf16_f32 v22, v22, v23
	v_cvt_pk_bf16_f32 v23, v24, v25
	global_store_dwordx2 v[38:39], v[22:23], off offset:64
	s_nop 3
	v_mov_b32_e32 v22, v152
	v_mov_b32_e32 v23, v153
	v_lshlrev_b32_e32 v24, 16, v22
	v_and_b32_e32 v25, 0xffff0000, v22
	v_lshlrev_b32_e32 v22, 16, v23
	v_and_b32_e32 v23, 0xffff0000, v23
	v_pk_mul_f32 v[18:19], v[18:19], v[24:25]
	v_pk_mul_f32 v[20:21], v[20:21], v[22:23]
	v_cvt_pk_bf16_f32 v18, v18, v19
	v_cvt_pk_bf16_f32 v19, v20, v21
	global_store_dwordx2 v[38:39], v[18:19], off offset:96
	s_nop 3
	v_mov_b32_e32 v18, v154
	v_mov_b32_e32 v19, v155
	v_lshlrev_b32_e32 v20, 16, v18
	v_and_b32_e32 v21, 0xffff0000, v18
	v_lshlrev_b32_e32 v18, 16, v19
	v_and_b32_e32 v19, 0xffff0000, v19
	v_pk_mul_f32 v[14:15], v[14:15], v[20:21]
	v_pk_mul_f32 v[16:17], v[16:17], v[18:19]
	v_cvt_pk_bf16_f32 v14, v14, v15
	v_cvt_pk_bf16_f32 v15, v16, v17
	global_store_dwordx2 v[38:39], v[14:15], off offset:128
	s_nop 3
	v_mov_b32_e32 v14, v156
	v_mov_b32_e32 v15, v157
	v_lshlrev_b32_e32 v16, 16, v14
	v_and_b32_e32 v17, 0xffff0000, v14
	v_lshlrev_b32_e32 v14, 16, v15
	v_and_b32_e32 v15, 0xffff0000, v15
	v_pk_mul_f32 v[10:11], v[10:11], v[16:17]
	v_pk_mul_f32 v[12:13], v[12:13], v[14:15]
	v_cvt_pk_bf16_f32 v10, v10, v11
	v_cvt_pk_bf16_f32 v11, v12, v13
	global_store_dwordx2 v[38:39], v[10:11], off offset:160
	s_nop 3
	v_mov_b32_e32 v10, v158
	v_mov_b32_e32 v11, v159
	v_lshlrev_b32_e32 v12, 16, v10
	v_and_b32_e32 v13, 0xffff0000, v10
	v_lshlrev_b32_e32 v10, 16, v11
	v_and_b32_e32 v11, 0xffff0000, v11
	v_pk_mul_f32 v[6:7], v[6:7], v[12:13]
	v_pk_mul_f32 v[8:9], v[8:9], v[10:11]
	v_cvt_pk_bf16_f32 v6, v6, v7
	v_cvt_pk_bf16_f32 v7, v8, v9
	global_store_dwordx2 v[38:39], v[6:7], off offset:192
	s_nop 3
	v_mov_b32_e32 v6, v160
	v_mov_b32_e32 v7, v161
	v_lshlrev_b32_e32 v8, 16, v6
	v_and_b32_e32 v9, 0xffff0000, v6
	v_lshlrev_b32_e32 v6, 16, v7
	v_and_b32_e32 v7, 0xffff0000, v7
	v_pk_mul_f32 v[2:3], v[2:3], v[8:9]
	v_pk_mul_f32 v[4:5], v[4:5], v[6:7]
	v_cvt_pk_bf16_f32 v2, v2, v3
	v_cvt_pk_bf16_f32 v3, v4, v5
	global_store_dwordx2 v[38:39], v[2:3], off offset:224

.Lf2_k:
	s_waitcnt vmcnt(0)
	s_barrier
	ds_read_b128 v[148:151], v80 offset:0
	ds_read_b128 v[152:155], v80 offset:2048
	ds_read_b128 v[156:159], v80 offset:4096
	ds_read_b128 v[160:163], v80 offset:6144
	ds_read_b128 v[188:191], v144 offset:32768
	ds_read_b128 v[192:195], v144 offset:34816
	ds_read_b128 v[208:211], v144 offset:36864
	ds_read_b128 v[212:215], v144 offset:38912
	ds_read_b128 v[164:167], v80 offset:16384
	ds_read_b128 v[168:171], v80 offset:18432
	ds_read_b128 v[174:177], v80 offset:20480
	ds_read_b128 v[182:185], v80 offset:22528
	s_add_i32 m0, s64, 0xc000
	s_nop 0
	global_load_lds_dwordx4 v76, s[58:59]
	s_add_i32 m0, s64, 0xd000
	s_nop 0
	global_load_lds_dwordx4 v77, s[58:59]
	s_add_i32 m0, s64, 0xe000
	s_nop 0
	global_load_lds_dwordx4 v78, s[58:59]
	s_add_i32 m0, s64, 0xf000
	s_nop 0
	global_load_lds_dwordx4 v79, s[58:59]
	s_add_u32 s58, s58, 0x80
	s_addc_u32 s59, s59, 0
	s_setprio 1
	s_waitcnt lgkmcnt(4)
	v_mfma_f32_16x16x32_bf16 v[62:65], v[188:191], v[148:151], v[62:65]
	v_mfma_f32_16x16x32_bf16 v[54:57], v[192:195], v[148:151], v[54:57]
	v_mfma_f32_16x16x32_bf16 v[58:61], v[208:211], v[148:151], v[58:61]
	v_mfma_f32_16x16x32_bf16 v[50:53], v[212:215], v[148:151], v[50:53]
	v_mfma_f32_16x16x32_bf16 v[46:49], v[188:191], v[152:155], v[46:49]
	v_mfma_f32_16x16x32_bf16 v[38:41], v[192:195], v[152:155], v[38:41]
	v_mfma_f32_16x16x32_bf16 v[42:45], v[208:211], v[152:155], v[42:45]
	v_mfma_f32_16x16x32_bf16 v[34:37], v[212:215], v[152:155], v[34:37]
	v_mfma_f32_16x16x32_bf16 v[30:33], v[188:191], v[156:159], v[30:33]
	v_mfma_f32_16x16x32_bf16 v[22:25], v[192:195], v[156:159], v[22:25]
	v_mfma_f32_16x16x32_bf16 v[26:29], v[208:211], v[156:159], v[26:29]
	v_mfma_f32_16x16x32_bf16 v[18:21], v[212:215], v[156:159], v[18:21]
	v_mfma_f32_16x16x32_bf16 v[14:17], v[188:191], v[160:163], v[14:17]
	v_mfma_f32_16x16x32_bf16 v[6:9], v[192:195], v[160:163], v[6:9]
	v_mfma_f32_16x16x32_bf16 v[10:13], v[208:211], v[160:163], v[10:13]
	v_mfma_f32_16x16x32_bf16 v[2:5], v[212:215], v[160:163], v[2:5]
	s_waitcnt lgkmcnt(0)
	v_mfma_f32_16x16x32_bf16 v[66:69], v[188:191], v[164:167], v[66:69]
	v_mfma_f32_16x16x32_bf16 v[70:73], v[192:195], v[164:167], v[70:73]
	v_mfma_f32_16x16x32_bf16 v[82:85], v[208:211], v[164:167], v[82:85]
	v_mfma_f32_16x16x32_bf16 v[86:89], v[212:215], v[164:167], v[86:89]
	v_mfma_f32_16x16x32_bf16 v[90:93], v[188:191], v[168:171], v[90:93]
	v_mfma_f32_16x16x32_bf16 v[94:97], v[192:195], v[168:171], v[94:97]
	v_mfma_f32_16x16x32_bf16 v[98:101], v[208:211], v[168:171], v[98:101]
	v_mfma_f32_16x16x32_bf16 v[102:105], v[212:215], v[168:171], v[102:105]
	v_mfma_f32_16x16x32_bf16 v[106:109], v[188:191], v[174:177], v[106:109]
	v_mfma_f32_16x16x32_bf16 v[110:113], v[192:195], v[174:177], v[110:113]
	v_mfma_f32_16x16x32_bf16 v[114:117], v[208:211], v[174:177], v[114:117]
	v_mfma_f32_16x16x32_bf16 v[118:121], v[212:215], v[174:177], v[118:121]
	v_mfma_f32_16x16x32_bf16 v[122:125], v[188:191], v[182:185], v[122:125]
	v_mfma_f32_16x16x32_bf16 v[126:129], v[192:195], v[182:185], v[126:129]
	v_mfma_f32_16x16x32_bf16 v[136:139], v[208:211], v[182:185], v[136:139]
	v_mfma_f32_16x16x32_bf16 v[140:143], v[212:215], v[182:185], v[140:143]
	s_setprio 0
	ds_read_b128 v[148:151], v81 offset:0
	ds_read_b128 v[152:155], v81 offset:2048
	ds_read_b128 v[156:159], v81 offset:4096
	ds_read_b128 v[160:163], v81 offset:6144
	ds_read_b128 v[188:191], v145 offset:32768
	ds_read_b128 v[192:195], v145 offset:34816
	ds_read_b128 v[208:211], v145 offset:36864
	ds_read_b128 v[212:215], v145 offset:38912
	ds_read_b128 v[164:167], v81 offset:16384
	ds_read_b128 v[168:171], v81 offset:18432
	ds_read_b128 v[174:177], v81 offset:20480
	ds_read_b128 v[182:185], v81 offset:22528
	s_waitcnt lgkmcnt(0)
	s_barrier
	s_add_i32 m0, s64, 0x0
	s_nop 0
	global_load_lds_dwordx4 v76, s[50:51]
	s_add_i32 m0, s64, 0x1000
	s_nop 0
	global_load_lds_dwordx4 v77, s[50:51]
	s_add_i32 m0, s64, 0x2000
	s_nop 0
	global_load_lds_dwordx4 v78, s[50:51]
	s_add_i32 m0, s64, 0x3000
	s_nop 0
	global_load_lds_dwordx4 v79, s[50:51]
	s_add_i32 m0, s64, 0x4000
	s_nop 0
	global_load_lds_dwordx4 v76, s[52:53]
	s_add_i32 m0, s64, 0x5000
	s_nop 0
	global_load_lds_dwordx4 v77, s[52:53]
	s_add_i32 m0, s64, 0x6000
	s_nop 0
	global_load_lds_dwordx4 v78, s[52:53]
	s_add_i32 m0, s64, 0x7000
	s_nop 0
	global_load_lds_dwordx4 v79, s[52:53]
	s_add_u32 s50, s50, 0x80
	s_addc_u32 s51, s51, 0
	s_add_u32 s52, s52, 0x80
	s_addc_u32 s53, s53, 0
	s_setprio 1
	v_mfma_f32_16x16x32_bf16 v[62:65], v[188:191], v[148:151], v[62:65]
	v_mfma_f32_16x16x32_bf16 v[54:57], v[192:195], v[148:151], v[54:57]
	v_mfma_f32_16x16x32_bf16 v[58:61], v[208:211], v[148:151], v[58:61]
	v_mfma_f32_16x16x32_bf16 v[50:53], v[212:215], v[148:151], v[50:53]
	v_mfma_f32_16x16x32_bf16 v[46:49], v[188:191], v[152:155], v[46:49]
	v_mfma_f32_16x16x32_bf16 v[38:41], v[192:195], v[152:155], v[38:41]
	v_mfma_f32_16x16x32_bf16 v[42:45], v[208:211], v[152:155], v[42:45]
	v_mfma_f32_16x16x32_bf16 v[34:37], v[212:215], v[152:155], v[34:37]
	v_mfma_f32_16x16x32_bf16 v[30:33], v[188:191], v[156:159], v[30:33]
	v_mfma_f32_16x16x32_bf16 v[22:25], v[192:195], v[156:159], v[22:25]
	v_mfma_f32_16x16x32_bf16 v[26:29], v[208:211], v[156:159], v[26:29]
	v_mfma_f32_16x16x32_bf16 v[18:21], v[212:215], v[156:159], v[18:21]
	v_mfma_f32_16x16x32_bf16 v[14:17], v[188:191], v[160:163], v[14:17]
	v_mfma_f32_16x16x32_bf16 v[6:9], v[192:195], v[160:163], v[6:9]
	v_mfma_f32_16x16x32_bf16 v[10:13], v[208:211], v[160:163], v[10:13]
	v_mfma_f32_16x16x32_bf16 v[2:5], v[212:215], v[160:163], v[2:5]
	v_mfma_f32_16x16x32_bf16 v[66:69], v[188:191], v[164:167], v[66:69]
	v_mfma_f32_16x16x32_bf16 v[70:73], v[192:195], v[164:167], v[70:73]
	v_mfma_f32_16x16x32_bf16 v[82:85], v[208:211], v[164:167], v[82:85]
	v_mfma_f32_16x16x32_bf16 v[86:89], v[212:215], v[164:167], v[86:89]
	v_mfma_f32_16x16x32_bf16 v[90:93], v[188:191], v[168:171], v[90:93]
	v_mfma_f32_16x16x32_bf16 v[94:97], v[192:195], v[168:171], v[94:97]
	v_mfma_f32_16x16x32_bf16 v[98:101], v[208:211], v[168:171], v[98:101]
	v_mfma_f32_16x16x32_bf16 v[102:105], v[212:215], v[168:171], v[102:105]
	v_mfma_f32_16x16x32_bf16 v[106:109], v[188:191], v[174:177], v[106:109]
	v_mfma_f32_16x16x32_bf16 v[110:113], v[192:195], v[174:177], v[110:113]
	v_mfma_f32_16x16x32_bf16 v[114:117], v[208:211], v[174:177], v[114:117]
	v_mfma_f32_16x16x32_bf16 v[118:121], v[212:215], v[174:177], v[118:121]
	v_mfma_f32_16x16x32_bf16 v[122:125], v[188:191], v[182:185], v[122:125]
	v_mfma_f32_16x16x32_bf16 v[126:129], v[192:195], v[182:185], v[126:129]
	v_mfma_f32_16x16x32_bf16 v[136:139], v[208:211], v[182:185], v[136:139]
	v_mfma_f32_16x16x32_bf16 v[140:143], v[212:215], v[182:185], v[140:143]
	s_setprio 0
	s_waitcnt vmcnt(0)
	s_barrier
	ds_read_b128 v[148:151], v80 offset:0
	ds_read_b128 v[152:155], v80 offset:2048
	ds_read_b128 v[156:159], v80 offset:4096
	ds_read_b128 v[160:163], v80 offset:6144
	ds_read_b128 v[188:191], v144 offset:49152
	ds_read_b128 v[192:195], v144 offset:51200
	ds_read_b128 v[208:211], v144 offset:53248
	ds_read_b128 v[212:215], v144 offset:55296
	ds_read_b128 v[164:167], v80 offset:16384
	ds_read_b128 v[168:171], v80 offset:18432
	ds_read_b128 v[174:177], v80 offset:20480
	ds_read_b128 v[182:185], v80 offset:22528
	s_add_i32 m0, s64, 0x8000
	s_nop 0
	global_load_lds_dwordx4 v76, s[58:59]
	s_add_i32 m0, s64, 0x9000
	s_nop 0
	global_load_lds_dwordx4 v77, s[58:59]
	s_add_i32 m0, s64, 0xa000
	s_nop 0
	global_load_lds_dwordx4 v78, s[58:59]
	s_add_i32 m0, s64, 0xb000
	s_nop 0
	global_load_lds_dwordx4 v79, s[58:59]
	s_add_u32 s58, s58, 0x80
	s_addc_u32 s59, s59, 0
	s_setprio 1
	s_waitcnt lgkmcnt(4)
	v_mfma_f32_16x16x32_bf16 v[62:65], v[188:191], v[148:151], v[62:65]
	v_mfma_f32_16x16x32_bf16 v[54:57], v[192:195], v[148:151], v[54:57]
	v_mfma_f32_16x16x32_bf16 v[58:61], v[208:211], v[148:151], v[58:61]
	v_mfma_f32_16x16x32_bf16 v[50:53], v[212:215], v[148:151], v[50:53]
	v_mfma_f32_16x16x32_bf16 v[46:49], v[188:191], v[152:155], v[46:49]
	v_mfma_f32_16x16x32_bf16 v[38:41], v[192:195], v[152:155], v[38:41]
	v_mfma_f32_16x16x32_bf16 v[42:45], v[208:211], v[152:155], v[42:45]
	v_mfma_f32_16x16x32_bf16 v[34:37], v[212:215], v[152:155], v[34:37]
	v_mfma_f32_16x16x32_bf16 v[30:33], v[188:191], v[156:159], v[30:33]
	v_mfma_f32_16x16x32_bf16 v[22:25], v[192:195], v[156:159], v[22:25]
	v_mfma_f32_16x16x32_bf16 v[26:29], v[208:211], v[156:159], v[26:29]
	v_mfma_f32_16x16x32_bf16 v[18:21], v[212:215], v[156:159], v[18:21]
	v_mfma_f32_16x16x32_bf16 v[14:17], v[188:191], v[160:163], v[14:17]
	v_mfma_f32_16x16x32_bf16 v[6:9], v[192:195], v[160:163], v[6:9]
	v_mfma_f32_16x16x32_bf16 v[10:13], v[208:211], v[160:163], v[10:13]
	v_mfma_f32_16x16x32_bf16 v[2:5], v[212:215], v[160:163], v[2:5]
	s_waitcnt lgkmcnt(0)
	v_mfma_f32_16x16x32_bf16 v[66:69], v[188:191], v[164:167], v[66:69]
	v_mfma_f32_16x16x32_bf16 v[70:73], v[192:195], v[164:167], v[70:73]
	v_mfma_f32_16x16x32_bf16 v[82:85], v[208:211], v[164:167], v[82:85]
	v_mfma_f32_16x16x32_bf16 v[86:89], v[212:215], v[164:167], v[86:89]
	v_mfma_f32_16x16x32_bf16 v[90:93], v[188:191], v[168:171], v[90:93]
	v_mfma_f32_16x16x32_bf16 v[94:97], v[192:195], v[168:171], v[94:97]
	v_mfma_f32_16x16x32_bf16 v[98:101], v[208:211], v[168:171], v[98:101]
	v_mfma_f32_16x16x32_bf16 v[102:105], v[212:215], v[168:171], v[102:105]
	v_mfma_f32_16x16x32_bf16 v[106:109], v[188:191], v[174:177], v[106:109]
	v_mfma_f32_16x16x32_bf16 v[110:113], v[192:195], v[174:177], v[110:113]
	v_mfma_f32_16x16x32_bf16 v[114:117], v[208:211], v[174:177], v[114:117]
	v_mfma_f32_16x16x32_bf16 v[118:121], v[212:215], v[174:177], v[118:121]
	v_mfma_f32_16x16x32_bf16 v[122:125], v[188:191], v[182:185], v[122:125]
	v_mfma_f32_16x16x32_bf16 v[126:129], v[192:195], v[182:185], v[126:129]
	v_mfma_f32_16x16x32_bf16 v[136:139], v[208:211], v[182:185], v[136:139]
	v_mfma_f32_16x16x32_bf16 v[140:143], v[212:215], v[182:185], v[140:143]
	s_setprio 0
	ds_read_b128 v[148:151], v81 offset:0
	ds_read_b128 v[152:155], v81 offset:2048
	ds_read_b128 v[156:159], v81 offset:4096
	ds_read_b128 v[160:163], v81 offset:6144
	ds_read_b128 v[188:191], v145 offset:49152
	ds_read_b128 v[192:195], v145 offset:51200
	ds_read_b128 v[208:211], v145 offset:53248
	ds_read_b128 v[212:215], v145 offset:55296
	ds_read_b128 v[164:167], v81 offset:16384
	ds_read_b128 v[168:171], v81 offset:18432
	ds_read_b128 v[174:177], v81 offset:20480
	ds_read_b128 v[182:185], v81 offset:22528
	s_waitcnt lgkmcnt(0)
	s_barrier
	s_add_i32 m0, s64, 0x0
	s_nop 0
	global_load_lds_dwordx4 v76, s[50:51]
	s_add_i32 m0, s64, 0x1000
	s_nop 0
	global_load_lds_dwordx4 v77, s[50:51]
	s_add_i32 m0, s64, 0x2000
	s_nop 0
	global_load_lds_dwordx4 v78, s[50:51]
	s_add_i32 m0, s64, 0x3000
	s_nop 0
	global_load_lds_dwordx4 v79, s[50:51]
	s_add_i32 m0, s64, 0x4000
	s_nop 0
	global_load_lds_dwordx4 v76, s[52:53]
	s_add_i32 m0, s64, 0x5000
	s_nop 0
	global_load_lds_dwordx4 v77, s[52:53]
	s_add_i32 m0, s64, 0x6000
	s_nop 0
	global_load_lds_dwordx4 v78, s[52:53]
	s_add_i32 m0, s64, 0x7000
	s_nop 0
	global_load_lds_dwordx4 v79, s[52:53]
	s_add_u32 s50, s50, 0x80
	s_addc_u32 s51, s51, 0
	s_add_u32 s52, s52, 0x80
	s_addc_u32 s53, s53, 0
	s_setprio 1
	v_mfma_f32_16x16x32_bf16 v[62:65], v[188:191], v[148:151], v[62:65]
	v_mfma_f32_16x16x32_bf16 v[54:57], v[192:195], v[148:151], v[54:57]
	v_mfma_f32_16x16x32_bf16 v[58:61], v[208:211], v[148:151], v[58:61]
	v_mfma_f32_16x16x32_bf16 v[50:53], v[212:215], v[148:151], v[50:53]
	v_mfma_f32_16x16x32_bf16 v[46:49], v[188:191], v[152:155], v[46:49]
	v_mfma_f32_16x16x32_bf16 v[38:41], v[192:195], v[152:155], v[38:41]
	v_mfma_f32_16x16x32_bf16 v[42:45], v[208:211], v[152:155], v[42:45]
	v_mfma_f32_16x16x32_bf16 v[34:37], v[212:215], v[152:155], v[34:37]
	v_mfma_f32_16x16x32_bf16 v[30:33], v[188:191], v[156:159], v[30:33]
	v_mfma_f32_16x16x32_bf16 v[22:25], v[192:195], v[156:159], v[22:25]
	v_mfma_f32_16x16x32_bf16 v[26:29], v[208:211], v[156:159], v[26:29]
	v_mfma_f32_16x16x32_bf16 v[18:21], v[212:215], v[156:159], v[18:21]
	v_mfma_f32_16x16x32_bf16 v[14:17], v[188:191], v[160:163], v[14:17]
	v_mfma_f32_16x16x32_bf16 v[6:9], v[192:195], v[160:163], v[6:9]
	v_mfma_f32_16x16x32_bf16 v[10:13], v[208:211], v[160:163], v[10:13]
	v_mfma_f32_16x16x32_bf16 v[2:5], v[212:215], v[160:163], v[2:5]
	v_mfma_f32_16x16x32_bf16 v[66:69], v[188:191], v[164:167], v[66:69]
	v_mfma_f32_16x16x32_bf16 v[70:73], v[192:195], v[164:167], v[70:73]
	v_mfma_f32_16x16x32_bf16 v[82:85], v[208:211], v[164:167], v[82:85]
	v_mfma_f32_16x16x32_bf16 v[86:89], v[212:215], v[164:167], v[86:89]
	v_mfma_f32_16x16x32_bf16 v[90:93], v[188:191], v[168:171], v[90:93]
	v_mfma_f32_16x16x32_bf16 v[94:97], v[192:195], v[168:171], v[94:97]
	v_mfma_f32_16x16x32_bf16 v[98:101], v[208:211], v[168:171], v[98:101]
	v_mfma_f32_16x16x32_bf16 v[102:105], v[212:215], v[168:171], v[102:105]
	v_mfma_f32_16x16x32_bf16 v[106:109], v[188:191], v[174:177], v[106:109]
	v_mfma_f32_16x16x32_bf16 v[110:113], v[192:195], v[174:177], v[110:113]
	v_mfma_f32_16x16x32_bf16 v[114:117], v[208:211], v[174:177], v[114:117]
	v_mfma_f32_16x16x32_bf16 v[118:121], v[212:215], v[174:177], v[118:121]
	v_mfma_f32_16x16x32_bf16 v[122:125], v[188:191], v[182:185], v[122:125]
	v_mfma_f32_16x16x32_bf16 v[126:129], v[192:195], v[182:185], v[126:129]
	v_mfma_f32_16x16x32_bf16 v[136:139], v[208:211], v[182:185], v[136:139]
	v_mfma_f32_16x16x32_bf16 v[140:143], v[212:215], v[182:185], v[140:143]
	s_setprio 0
	s_add_i32 s65, s65, -1
	s_cmp_lg_u32 s65, 0
	s_cbranch_scc1 .Lf2_k
	s_waitcnt vmcnt(0)
	s_barrier
	ds_read_b128 v[148:151], v80 offset:0
	ds_read_b128 v[152:155], v80 offset:2048
	ds_read_b128 v[156:159], v80 offset:4096
	ds_read_b128 v[160:163], v80 offset:6144
	ds_read_b128 v[188:191], v144 offset:32768
	ds_read_b128 v[192:195], v144 offset:34816
	ds_read_b128 v[208:211], v144 offset:36864
	ds_read_b128 v[212:215], v144 offset:38912
	ds_read_b128 v[164:167], v80 offset:16384
	ds_read_b128 v[168:171], v80 offset:18432
	ds_read_b128 v[174:177], v80 offset:20480
	ds_read_b128 v[182:185], v80 offset:22528
	s_add_i32 m0, s64, 0xc000
	s_nop 0
	global_load_lds_dwordx4 v76, s[58:59]
	s_add_i32 m0, s64, 0xd000
	s_nop 0
	global_load_lds_dwordx4 v77, s[58:59]
	s_add_i32 m0, s64, 0xe000
	s_nop 0
	global_load_lds_dwordx4 v78, s[58:59]
	s_add_i32 m0, s64, 0xf000
	s_nop 0
	global_load_lds_dwordx4 v79, s[58:59]
	s_add_u32 s58, s58, 0x80
	s_addc_u32 s59, s59, 0
	s_setprio 1
	s_waitcnt lgkmcnt(4)
	v_mfma_f32_16x16x32_bf16 v[62:65], v[188:191], v[148:151], v[62:65]
	v_mfma_f32_16x16x32_bf16 v[54:57], v[192:195], v[148:151], v[54:57]
	v_mfma_f32_16x16x32_bf16 v[58:61], v[208:211], v[148:151], v[58:61]
	v_mfma_f32_16x16x32_bf16 v[50:53], v[212:215], v[148:151], v[50:53]
	v_mfma_f32_16x16x32_bf16 v[46:49], v[188:191], v[152:155], v[46:49]
	v_mfma_f32_16x16x32_bf16 v[38:41], v[192:195], v[152:155], v[38:41]
	v_mfma_f32_16x16x32_bf16 v[42:45], v[208:211], v[152:155], v[42:45]
	v_mfma_f32_16x16x32_bf16 v[34:37], v[212:215], v[152:155], v[34:37]
	v_mfma_f32_16x16x32_bf16 v[30:33], v[188:191], v[156:159], v[30:33]
	v_mfma_f32_16x16x32_bf16 v[22:25], v[192:195], v[156:159], v[22:25]
	v_mfma_f32_16x16x32_bf16 v[26:29], v[208:211], v[156:159], v[26:29]
	v_mfma_f32_16x16x32_bf16 v[18:21], v[212:215], v[156:159], v[18:21]
	v_mfma_f32_16x16x32_bf16 v[14:17], v[188:191], v[160:163], v[14:17]
	v_mfma_f32_16x16x32_bf16 v[6:9], v[192:195], v[160:163], v[6:9]
	v_mfma_f32_16x16x32_bf16 v[10:13], v[208:211], v[160:163], v[10:13]
	v_mfma_f32_16x16x32_bf16 v[2:5], v[212:215], v[160:163], v[2:5]
	s_waitcnt lgkmcnt(0)
	v_mfma_f32_16x16x32_bf16 v[66:69], v[188:191], v[164:167], v[66:69]
	v_mfma_f32_16x16x32_bf16 v[70:73], v[192:195], v[164:167], v[70:73]
	v_mfma_f32_16x16x32_bf16 v[82:85], v[208:211], v[164:167], v[82:85]
	v_mfma_f32_16x16x32_bf16 v[86:89], v[212:215], v[164:167], v[86:89]
	v_mfma_f32_16x16x32_bf16 v[90:93], v[188:191], v[168:171], v[90:93]
	v_mfma_f32_16x16x32_bf16 v[94:97], v[192:195], v[168:171], v[94:97]
	v_mfma_f32_16x16x32_bf16 v[98:101], v[208:211], v[168:171], v[98:101]
	v_mfma_f32_16x16x32_bf16 v[102:105], v[212:215], v[168:171], v[102:105]
	v_mfma_f32_16x16x32_bf16 v[106:109], v[188:191], v[174:177], v[106:109]
	v_mfma_f32_16x16x32_bf16 v[110:113], v[192:195], v[174:177], v[110:113]
	v_mfma_f32_16x16x32_bf16 v[114:117], v[208:211], v[174:177], v[114:117]
	v_mfma_f32_16x16x32_bf16 v[118:121], v[212:215], v[174:177], v[118:121]
	v_mfma_f32_16x16x32_bf16 v[122:125], v[188:191], v[182:185], v[122:125]
	v_mfma_f32_16x16x32_bf16 v[126:129], v[192:195], v[182:185], v[126:129]
	v_mfma_f32_16x16x32_bf16 v[136:139], v[208:211], v[182:185], v[136:139]
	v_mfma_f32_16x16x32_bf16 v[140:143], v[212:215], v[182:185], v[140:143]
	s_setprio 0
	ds_read_b128 v[148:151], v81 offset:0
	ds_read_b128 v[152:155], v81 offset:2048
	ds_read_b128 v[156:159], v81 offset:4096
	ds_read_b128 v[160:163], v81 offset:6144
	ds_read_b128 v[188:191], v145 offset:32768
	ds_read_b128 v[192:195], v145 offset:34816
	ds_read_b128 v[208:211], v145 offset:36864
	ds_read_b128 v[212:215], v145 offset:38912
	ds_read_b128 v[164:167], v81 offset:16384
	ds_read_b128 v[168:171], v81 offset:18432
	ds_read_b128 v[174:177], v81 offset:20480
	ds_read_b128 v[182:185], v81 offset:22528
	s_waitcnt lgkmcnt(0)
	s_barrier
	s_add_i32 m0, s64, 0x0
	s_nop 0
	global_load_lds_dwordx4 v76, s[50:51]
	s_add_i32 m0, s64, 0x1000
	s_nop 0
	global_load_lds_dwordx4 v77, s[50:51]
	s_add_i32 m0, s64, 0x2000
	s_nop 0
	global_load_lds_dwordx4 v78, s[50:51]
	s_add_i32 m0, s64, 0x3000
	s_nop 0
	global_load_lds_dwordx4 v79, s[50:51]
	s_add_i32 m0, s64, 0x4000
	s_nop 0
	global_load_lds_dwordx4 v76, s[52:53]
	s_add_i32 m0, s64, 0x5000
	s_nop 0
	global_load_lds_dwordx4 v77, s[52:53]
	s_add_i32 m0, s64, 0x6000
	s_nop 0
	global_load_lds_dwordx4 v78, s[52:53]
	s_add_i32 m0, s64, 0x7000
	s_nop 0
	global_load_lds_dwordx4 v79, s[52:53]
	s_add_u32 s50, s50, 0x80
	s_addc_u32 s51, s51, 0
	s_add_u32 s52, s52, 0x80
	s_addc_u32 s53, s53, 0
	s_setprio 1
	v_mfma_f32_16x16x32_bf16 v[62:65], v[188:191], v[148:151], v[62:65]
	v_mfma_f32_16x16x32_bf16 v[54:57], v[192:195], v[148:151], v[54:57]
	v_mfma_f32_16x16x32_bf16 v[58:61], v[208:211], v[148:151], v[58:61]
	v_mfma_f32_16x16x32_bf16 v[50:53], v[212:215], v[148:151], v[50:53]
	v_mfma_f32_16x16x32_bf16 v[46:49], v[188:191], v[152:155], v[46:49]
	v_mfma_f32_16x16x32_bf16 v[38:41], v[192:195], v[152:155], v[38:41]
	v_mfma_f32_16x16x32_bf16 v[42:45], v[208:211], v[152:155], v[42:45]
	v_mfma_f32_16x16x32_bf16 v[34:37], v[212:215], v[152:155], v[34:37]
	v_mfma_f32_16x16x32_bf16 v[30:33], v[188:191], v[156:159], v[30:33]
	v_mfma_f32_16x16x32_bf16 v[22:25], v[192:195], v[156:159], v[22:25]
	v_mfma_f32_16x16x32_bf16 v[26:29], v[208:211], v[156:159], v[26:29]
	v_mfma_f32_16x16x32_bf16 v[18:21], v[212:215], v[156:159], v[18:21]
	v_mfma_f32_16x16x32_bf16 v[14:17], v[188:191], v[160:163], v[14:17]
	v_mfma_f32_16x16x32_bf16 v[6:9], v[192:195], v[160:163], v[6:9]
	v_mfma_f32_16x16x32_bf16 v[10:13], v[208:211], v[160:163], v[10:13]
	v_mfma_f32_16x16x32_bf16 v[2:5], v[212:215], v[160:163], v[2:5]
	v_mfma_f32_16x16x32_bf16 v[66:69], v[188:191], v[164:167], v[66:69]
	v_mfma_f32_16x16x32_bf16 v[70:73], v[192:195], v[164:167], v[70:73]
	v_mfma_f32_16x16x32_bf16 v[82:85], v[208:211], v[164:167], v[82:85]
	v_mfma_f32_16x16x32_bf16 v[86:89], v[212:215], v[164:167], v[86:89]
	v_mfma_f32_16x16x32_bf16 v[90:93], v[188:191], v[168:171], v[90:93]
	v_mfma_f32_16x16x32_bf16 v[94:97], v[192:195], v[168:171], v[94:97]
	v_mfma_f32_16x16x32_bf16 v[98:101], v[208:211], v[168:171], v[98:101]
	v_mfma_f32_16x16x32_bf16 v[102:105], v[212:215], v[168:171], v[102:105]
	v_mfma_f32_16x16x32_bf16 v[106:109], v[188:191], v[174:177], v[106:109]
	v_mfma_f32_16x16x32_bf16 v[110:113], v[192:195], v[174:177], v[110:113]
	v_mfma_f32_16x16x32_bf16 v[114:117], v[208:211], v[174:177], v[114:117]
	v_mfma_f32_16x16x32_bf16 v[118:121], v[212:215], v[174:177], v[118:121]
	v_mfma_f32_16x16x32_bf16 v[122:125], v[188:191], v[182:185], v[122:125]
	v_mfma_f32_16x16x32_bf16 v[126:129], v[192:195], v[182:185], v[126:129]
	v_mfma_f32_16x16x32_bf16 v[136:139], v[208:211], v[182:185], v[136:139]
	v_mfma_f32_16x16x32_bf16 v[140:143], v[212:215], v[182:185], v[140:143]
	s_setprio 0
	s_waitcnt vmcnt(0)
	s_barrier
	ds_read_b128 v[148:151], v80 offset:0
	ds_read_b128 v[152:155], v80 offset:2048
	ds_read_b128 v[156:159], v80 offset:4096
	ds_read_b128 v[160:163], v80 offset:6144
	ds_read_b128 v[188:191], v144 offset:49152
	ds_read_b128 v[192:195], v144 offset:51200
	ds_read_b128 v[208:211], v144 offset:53248
	ds_read_b128 v[212:215], v144 offset:55296
	ds_read_b128 v[164:167], v80 offset:16384
	ds_read_b128 v[168:171], v80 offset:18432
	ds_read_b128 v[174:177], v80 offset:20480
	ds_read_b128 v[182:185], v80 offset:22528
	s_setprio 1
	s_waitcnt lgkmcnt(4)
	v_mfma_f32_16x16x32_bf16 v[62:65], v[188:191], v[148:151], v[62:65]
	v_mfma_f32_16x16x32_bf16 v[54:57], v[192:195], v[148:151], v[54:57]
	v_mfma_f32_16x16x32_bf16 v[58:61], v[208:211], v[148:151], v[58:61]
	v_mfma_f32_16x16x32_bf16 v[50:53], v[212:215], v[148:151], v[50:53]
	v_mfma_f32_16x16x32_bf16 v[46:49], v[188:191], v[152:155], v[46:49]
	v_mfma_f32_16x16x32_bf16 v[38:41], v[192:195], v[152:155], v[38:41]
	v_mfma_f32_16x16x32_bf16 v[42:45], v[208:211], v[152:155], v[42:45]
	v_mfma_f32_16x16x32_bf16 v[34:37], v[212:215], v[152:155], v[34:37]
	v_mfma_f32_16x16x32_bf16 v[30:33], v[188:191], v[156:159], v[30:33]
	v_mfma_f32_16x16x32_bf16 v[22:25], v[192:195], v[156:159], v[22:25]
	v_mfma_f32_16x16x32_bf16 v[26:29], v[208:211], v[156:159], v[26:29]
	v_mfma_f32_16x16x32_bf16 v[18:21], v[212:215], v[156:159], v[18:21]
	v_mfma_f32_16x16x32_bf16 v[14:17], v[188:191], v[160:163], v[14:17]
	v_mfma_f32_16x16x32_bf16 v[6:9], v[192:195], v[160:163], v[6:9]
	v_mfma_f32_16x16x32_bf16 v[10:13], v[208:211], v[160:163], v[10:13]
	v_mfma_f32_16x16x32_bf16 v[2:5], v[212:215], v[160:163], v[2:5]
	s_waitcnt lgkmcnt(0)
	v_mfma_f32_16x16x32_bf16 v[66:69], v[188:191], v[164:167], v[66:69]
	v_mfma_f32_16x16x32_bf16 v[70:73], v[192:195], v[164:167], v[70:73]
	v_mfma_f32_16x16x32_bf16 v[82:85], v[208:211], v[164:167], v[82:85]
	v_mfma_f32_16x16x32_bf16 v[86:89], v[212:215], v[164:167], v[86:89]
	v_mfma_f32_16x16x32_bf16 v[90:93], v[188:191], v[168:171], v[90:93]
	v_mfma_f32_16x16x32_bf16 v[94:97], v[192:195], v[168:171], v[94:97]
	v_mfma_f32_16x16x32_bf16 v[98:101], v[208:211], v[168:171], v[98:101]
	v_mfma_f32_16x16x32_bf16 v[102:105], v[212:215], v[168:171], v[102:105]
	v_mfma_f32_16x16x32_bf16 v[106:109], v[188:191], v[174:177], v[106:109]
	v_mfma_f32_16x16x32_bf16 v[110:113], v[192:195], v[174:177], v[110:113]
	v_mfma_f32_16x16x32_bf16 v[114:117], v[208:211], v[174:177], v[114:117]
	v_mfma_f32_16x16x32_bf16 v[118:121], v[212:215], v[174:177], v[118:121]
	v_mfma_f32_16x16x32_bf16 v[122:125], v[188:191], v[182:185], v[122:125]
	v_mfma_f32_16x16x32_bf16 v[126:129], v[192:195], v[182:185], v[126:129]
	v_mfma_f32_16x16x32_bf16 v[136:139], v[208:211], v[182:185], v[136:139]
	v_mfma_f32_16x16x32_bf16 v[140:143], v[212:215], v[182:185], v[140:143]
	s_setprio 0
	ds_read_b128 v[148:151], v81 offset:0
	ds_read_b128 v[152:155], v81 offset:2048
	ds_read_b128 v[156:159], v81 offset:4096
	ds_read_b128 v[160:163], v81 offset:6144
	ds_read_b128 v[188:191], v145 offset:49152
	ds_read_b128 v[192:195], v145 offset:51200
	ds_read_b128 v[208:211], v145 offset:53248
	ds_read_b128 v[212:215], v145 offset:55296
	ds_read_b128 v[164:167], v81 offset:16384
	ds_read_b128 v[168:171], v81 offset:18432
	ds_read_b128 v[174:177], v81 offset:20480
	ds_read_b128 v[182:185], v81 offset:22528
	s_setprio 1
	s_waitcnt lgkmcnt(4)
	v_mfma_f32_16x16x32_bf16 v[62:65], v[188:191], v[148:151], v[62:65]
	v_mfma_f32_16x16x32_bf16 v[54:57], v[192:195], v[148:151], v[54:57]
	v_mfma_f32_16x16x32_bf16 v[58:61], v[208:211], v[148:151], v[58:61]
	v_mfma_f32_16x16x32_bf16 v[50:53], v[212:215], v[148:151], v[50:53]
	v_mfma_f32_16x16x32_bf16 v[46:49], v[188:191], v[152:155], v[46:49]
	v_mfma_f32_16x16x32_bf16 v[38:41], v[192:195], v[152:155], v[38:41]
	v_mfma_f32_16x16x32_bf16 v[42:45], v[208:211], v[152:155], v[42:45]
	v_mfma_f32_16x16x32_bf16 v[34:37], v[212:215], v[152:155], v[34:37]
	v_mfma_f32_16x16x32_bf16 v[30:33], v[188:191], v[156:159], v[30:33]
	v_mfma_f32_16x16x32_bf16 v[22:25], v[192:195], v[156:159], v[22:25]
	v_mfma_f32_16x16x32_bf16 v[26:29], v[208:211], v[156:159], v[26:29]
	v_mfma_f32_16x16x32_bf16 v[18:21], v[212:215], v[156:159], v[18:21]
	v_mfma_f32_16x16x32_bf16 v[14:17], v[188:191], v[160:163], v[14:17]
	v_mfma_f32_16x16x32_bf16 v[6:9], v[192:195], v[160:163], v[6:9]
	v_mfma_f32_16x16x32_bf16 v[10:13], v[208:211], v[160:163], v[10:13]
	v_mfma_f32_16x16x32_bf16 v[2:5], v[212:215], v[160:163], v[2:5]
	s_waitcnt lgkmcnt(0)
	v_mfma_f32_16x16x32_bf16 v[66:69], v[188:191], v[164:167], v[66:69]
	v_mfma_f32_16x16x32_bf16 v[70:73], v[192:195], v[164:167], v[70:73]
	v_mfma_f32_16x16x32_bf16 v[82:85], v[208:211], v[164:167], v[82:85]
	v_mfma_f32_16x16x32_bf16 v[86:89], v[212:215], v[164:167], v[86:89]
	v_mfma_f32_16x16x32_bf16 v[90:93], v[188:191], v[168:171], v[90:93]
	v_mfma_f32_16x16x32_bf16 v[94:97], v[192:195], v[168:171], v[94:97]
	v_mfma_f32_16x16x32_bf16 v[98:101], v[208:211], v[168:171], v[98:101]
	v_mfma_f32_16x16x32_bf16 v[102:105], v[212:215], v[168:171], v[102:105]
	v_mfma_f32_16x16x32_bf16 v[106:109], v[188:191], v[174:177], v[106:109]
	v_mfma_f32_16x16x32_bf16 v[110:113], v[192:195], v[174:177], v[110:113]
	v_mfma_f32_16x16x32_bf16 v[114:117], v[208:211], v[174:177], v[114:117]
	v_mfma_f32_16x16x32_bf16 v[118:121], v[212:215], v[174:177], v[118:121]
	v_mfma_f32_16x16x32_bf16 v[122:125], v[188:191], v[182:185], v[122:125]
	v_mfma_f32_16x16x32_bf16 v[126:129], v[192:195], v[182:185], v[126:129]
	v_mfma_f32_16x16x32_bf16 v[136:139], v[208:211], v[182:185], v[136:139]
	v_mfma_f32_16x16x32_bf16 v[140:143], v[212:215], v[182:185], v[140:143]
	s_setprio 0
	s_nop 7
	s_nop 7
	s_nop 7
	v_mov_b32_e32 v148, v66
	v_mov_b32_e32 v149, v67
	v_mov_b32_e32 v150, v68
	v_mov_b32_e32 v151, v69
	v_mov_b32_e32 v152, v70
	v_mov_b32_e32 v153, v71
	v_mov_b32_e32 v154, v72
	v_mov_b32_e32 v155, v73
	v_mov_b32_e32 v156, v82
	v_mov_b32_e32 v157, v83
	v_mov_b32_e32 v158, v84
	v_mov_b32_e32 v159, v85
	v_mov_b32_e32 v160, v86
	v_mov_b32_e32 v161, v87
	v_mov_b32_e32 v162, v88
	v_mov_b32_e32 v163, v89
	v_mov_b32_e32 v164, v90
	v_mov_b32_e32 v165, v91
	v_mov_b32_e32 v166, v92
	v_mov_b32_e32 v167, v93
	v_mov_b32_e32 v168, v94
	v_mov_b32_e32 v169, v95
	v_mov_b32_e32 v170, v96
	v_mov_b32_e32 v171, v97
	v_mov_b32_e32 v174, v98
	v_mov_b32_e32 v175, v99
	v_mov_b32_e32 v176, v100
	v_mov_b32_e32 v177, v101
	v_mov_b32_e32 v182, v102
	v_mov_b32_e32 v183, v103
	v_mov_b32_e32 v184, v104
	v_mov_b32_e32 v185, v105
	v_mov_b32_e32 v188, v106
	v_mov_b32_e32 v189, v107
	v_mov_b32_e32 v190, v108
	v_mov_b32_e32 v191, v109
	v_mov_b32_e32 v192, v110
	v_mov_b32_e32 v193, v111
	v_mov_b32_e32 v194, v112
	v_mov_b32_e32 v195, v113
	v_mov_b32_e32 v208, v114
	v_mov_b32_e32 v209, v115
	v_mov_b32_e32 v210, v116
	v_mov_b32_e32 v211, v117
	v_mov_b32_e32 v212, v118
	v_mov_b32_e32 v213, v119
	v_mov_b32_e32 v214, v120
	v_mov_b32_e32 v215, v121
	v_mov_b32_e32 v216, v122
	v_mov_b32_e32 v217, v123
	v_mov_b32_e32 v218, v124
	v_mov_b32_e32 v219, v125
	v_mov_b32_e32 v220, v126
	v_mov_b32_e32 v221, v127
	v_mov_b32_e32 v222, v128
	v_mov_b32_e32 v223, v129
	v_mov_b32_e32 v242, v136
	v_mov_b32_e32 v243, v137
	v_mov_b32_e32 v244, v138
	v_mov_b32_e32 v245, v139
	v_mov_b32_e32 v199, v140
	v_mov_b32_e32 v206, v141
	v_mov_b32_e32 v207, v142
	v_mov_b32_e32 v226, v143
	s_add_i32 s48, s48, 1
	s_mov_b32 s39, 0
	v_readlane_b32 s30, v249, 0
	s_nop 0
	s_and_b32 s31, s30, 7
	s_lshr_b32 s30, s30, 3
	s_cmp_lt_u32 s30, 32
	s_cselect_b32 s35, 6, 5
	s_cmp_lt_u32 s48, s35
	s_cbranch_scc0 .Lf2_c1_extra
	s_lshl_b32 s33, s48, 6
	s_add_i32 s33, s33, s30
	s_cmp_ge_u32 s33, 0xb0
	s_cselect_b32 s34, 1, 0
	s_mul_i32 s36, s34, 0xb0
	s_sub_i32 s33, s33, s36
	s_lshr_b32 s37, s33, 2
	s_and_b32 s33, s33, 3
	s_lshl_b32 s34, s34, 3
	s_add_i32 s33, s33, s34
	s_lshl_b32 s33, s33, 3
	s_add_i32 s36, s33, s31
	s_add_i32 s38, s36, 32
	s_branch .Lf2_c1_have
